# GDN chunk prep: forward substitution (I+A)^-1 rewritten for all 8 waves (direction x 16-column block per wave, 4 k-slices per column in adjacent lanes, quad DPP reduce), f32 as before
# speedup vs baseline: 1.0175x; 1.0148x over previous
; #define LAS __attribute__((address_space(3)))
; __device__ __forceinline__ float fexp(float x) { return __builtin_amdgcn_exp2f(x * 1.4426950408889634f); }
; __device__ __forceinline__ v2u pack4(const f32x4 v) { v2u r; r.x = pk2(v[0], v[1]); r.y = pk2(v[2], v[3]); return r; }
;     ...
;     for (int k2 = 0; k2 < 2; ++k2) {
;         const int tt = 2 * w + k2, mt = tt >> 2, nt = tt & 3;
;         f32x4 accG = {0.f, 0.f, 0.f, 0.f}, accQ = {0.f, 0.f, 0.f, 0.f};
;         accG = mma_ll<2>(Ks + mt * 16 * 72, 72, Ks + nt * 16 * 72, 72, accG, lane);
;         accQ = mma_ll<2>(Ks + mt * 16 * 72, 72, Qs + nt * 16 * 72, 72, accQ, lane);
;         const int n = nt * 16 + lr, m0 = mt * 16 + 4 * lq;
; #pragma unroll
;         for (int d = 0; d < 2; ++d) {
;             const float gcn = gcS[d * 64 + n], bn = bS[d * 64 + n];
;             f32x4 av, tv;
; #pragma unroll
;             for (int i = 0; i < 4; ++i) { const int m = m0 + i; const float gcm = gcS[d * 64 + m];
;                 const bool strict = d == 0 ? (m < n) : (m > n); const bool incl = d == 0 ? (m <= n) : (m >= n);
;                 const float e = fexp(incl ? (gcn - gcm) : 0.f);
;                 av[i] = strict ? bn * accG[i] * e : 0.f; tv[i] = incl ? 0.125f * accQ[i] * e : 0.f; }
; #pragma unroll
;             for (int i = 0; i < 4; ++i) { const int si = d ? 63 - n : n, sj = d ? 63 - (m0 + i) : m0 + i; As[d * 4352 + (si >> 1) * 136 + sj * 2 + (si & 1)] = av[i]; }
;             *(LAS v2u*)(At + d * 4608 + n * 72 + m0) = pack4(tv);
;         }
;     }
.LBB0_642:
	s_lshl_b32 s0, s28, 1
	s_and_b32 s1, s0, 2
	s_lshl_b32 s0, s28, 3
	s_and_b32 s3, s0, -16
	v_lshrrev_b32_e32 v7, 1, v52
	v_and_b32_e32 v109, 15, v52
	s_mul_i32 s4, s3, 0x90
	v_and_b32_e32 v0, 24, v7
	v_lshrrev_b32_e32 v13, 4, v53
	s_add_i32 s4, s4, 0
	v_mul_u32_u24_e32 v113, 0x90, v109
	v_lshlrev_b32_e32 v117, 1, v0
	v_add3_u32 v12, s4, v113, v117
	s_movk_i32 s4, 0x90
	v_lshlrev_b32_e32 v17, 2, v13
	v_mad_u32_u24 v121, v109, s4, 0
	v_or_b32_e32 v15, s3, v17
	v_readlane_b32 s3, v253, 55
	v_add_u32_e32 v14, v121, v117
	s_waitcnt lgkmcnt(0)
	v_lshl_add_u32 v16, v15, 1, s3
	s_mul_i32 s3, s1, 0x900
	s_barrier
	v_add_u32_e32 v6, s3, v14
	ds_read_b128 v[8:11], v12 offset:9216
	ds_read_b128 v[2:5], v6 offset:9216
	ds_read_b128 v[22:25], v12 offset:9280
	ds_read_b128 v[26:29], v6 offset:9280
	s_waitcnt lgkmcnt(2)
	v_mfma_f32_16x16x32_bf16 v[2:5], v[8:11], v[2:5], 0
	v_lshl_or_b32 v20, s1, 4, v109
	v_cmp_gt_i32_e64 s[40:41], v15, v20
	v_cmp_lt_i32_e32 vcc, v15, v20
	s_waitcnt lgkmcnt(0)
	v_mfma_f32_16x16x32_bf16 v[2:5], v[22:25], v[26:29], v[2:5]
	ds_read_b128 v[26:29], v6
	v_or_b32_e32 v34, 2, v15
	v_cmp_gt_i32_e64 s[46:47], v34, v20
	s_waitcnt lgkmcnt(0)
	v_mfma_f32_16x16x32_bf16 v[8:11], v[8:11], v[26:29], 0
	ds_read_b128 v[26:29], v6 offset:64
	v_lshl_add_u32 v6, v15, 2, 0
	v_or_b32_e32 v36, 3, v15
	s_waitcnt lgkmcnt(0)
	v_mfma_f32_16x16x32_bf16 v[8:11], v[22:25], v[26:29], v[8:11]
	v_lshl_add_u32 v27, v20, 2, 0
	ds_read_b32 v28, v27 offset:37888
	ds_read_b32 v29, v27 offset:37376
	ds_read_b128 v[22:25], v6 offset:37888
	s_nop 3
	v_mul_f32_e32 v31, 0x3e000000, v8
	v_mul_f32_e32 v33, 0x3e000000, v9
	v_mul_f32_e32 v35, 0x3e000000, v10
	s_waitcnt lgkmcnt(1)
	v_mul_f32_e32 v30, v2, v29
	s_waitcnt lgkmcnt(0)
	v_sub_f32_e32 v22, v28, v22
	v_mul_f32_e32 v22, 0x3fb8aa3b, v22
	v_cndmask_b32_e64 v22, v22, 0, s[40:41]
	v_exp_f32_e32 v22, v22
	v_cmp_gt_i32_e64 s[50:51], v36, v20
	v_or_b32_e32 v32, 1, v15
	v_and_b32_e32 v18, 1, v52
	v_mul_f32_e32 v30, v30, v22
	v_mul_f32_e32 v8, v31, v22
	v_sub_f32_e32 v22, v28, v23
	v_mul_f32_e32 v22, 0x3fb8aa3b, v22
	v_cndmask_b32_e32 v22, 0, v22, vcc
	v_exp_f32_e32 v22, v22
	v_mul_f32_e32 v23, v3, v29
	v_mad_u32_u24 v26, v20, s4, v16
	v_cmp_lt_i32_e64 s[42:43], v32, v20
	v_mul_f32_e32 v23, v23, v22
	v_mul_f32_e32 v9, v33, v22
	v_sub_f32_e32 v22, v28, v24
	v_mul_f32_e32 v22, 0x3fb8aa3b, v22
	v_cndmask_b32_e64 v22, v22, 0, s[46:47]
	v_exp_f32_e32 v22, v22
	v_mul_f32_e32 v24, v4, v29
	v_cmp_lt_i32_e64 s[44:45], v34, v20
	v_cmp_lt_i32_e64 s[48:49], v36, v20
	v_mul_f32_e32 v24, v24, v22
	v_mul_f32_e32 v10, v35, v22
	v_sub_f32_e32 v22, v28, v25
	v_mul_f32_e32 v22, 0x3fb8aa3b, v22
	v_cndmask_b32_e64 v22, v22, 0, s[50:51]
	v_exp_f32_e32 v22, v22
	v_mul_f32_e32 v25, v5, v29
	v_mul_f32_e32 v28, 0x3e000000, v11
	v_lshrrev_b32_e32 v20, 1, v20
	v_mul_f32_e32 v25, v25, v22
	v_mul_f32_e32 v11, v28, v22
	v_mul_u32_u24_e32 v22, 0x220, v20
	v_lshlrev_b32_e32 v18, 2, v18
	v_lshlrev_b32_e32 v0, 3, v15
	v_add3_u32 v22, 0, v22, v18
	v_cndmask_b32_e32 v30, 0, v30, vcc
	v_add_u32_e32 v29, v22, v0
	ds_write_b32 v29, v30 offset:38912
	v_lshlrev_b32_e32 v30, 3, v32
	v_cndmask_b32_e64 v8, v8, 0, s[40:41]
	v_cndmask_b32_e64 v23, 0, v23, s[42:43]
	v_cndmask_b32_e32 v9, 0, v9, vcc
	v_cndmask_b32_e64 v10, v10, 0, s[46:47]
	v_cndmask_b32_e64 v11, v11, 0, s[50:51]
	v_add_u32_e32 v29, v22, v30
	v_lshlrev_b32_e32 v37, 3, v34
	v_lshlrev_b32_e32 v38, 3, v36
	v_cndmask_b32_e64 v24, 0, v24, s[44:45]
	v_cndmask_b32_e64 v25, 0, v25, s[48:49]
	ds_write_b32 v29, v23 offset:38912
	v_add_u32_e32 v23, v22, v37
	v_add_u32_e32 v22, v22, v38
	v_cvt_pk_bf16_f32 v8, v8, v9
	v_cvt_pk_bf16_f32 v9, v10, v11
	ds_write_b32 v23, v24 offset:38912
	ds_write_b32 v22, v25 offset:38912
	ds_write_b64 v26, v[8:9]
	ds_read_b32 v22, v27 offset:38144
	ds_read_b32 v23, v27 offset:37632
	ds_read_b128 v[8:11], v6 offset:38144
	v_bitop3_b32 v19, v52, 1, v52 bitop3:0xc
	v_xor_b32_e32 v20, 31, v20
	v_mul_u32_u24_e32 v20, 0x220, v20
	s_waitcnt lgkmcnt(1)
	v_mul_f32_e32 v2, v2, v23
	s_waitcnt lgkmcnt(0)
	v_sub_f32_e32 v8, v22, v8
	v_mul_f32_e32 v8, 0x3fb8aa3b, v8
	v_sub_f32_e32 v9, v22, v9
	v_cndmask_b32_e64 v8, v8, 0, vcc
	v_mul_f32_e32 v9, 0x3fb8aa3b, v9
	v_sub_f32_e32 v10, v22, v10
	v_exp_f32_e32 v8, v8
	v_cndmask_b32_e64 v9, v9, 0, s[42:43]
	v_mul_f32_e32 v10, 0x3fb8aa3b, v10
	v_sub_f32_e32 v11, v22, v11
	v_exp_f32_e32 v9, v9
	v_cndmask_b32_e64 v10, v10, 0, s[44:45]
	v_mul_f32_e32 v11, 0x3fb8aa3b, v11
	v_exp_f32_e32 v10, v10
	v_cndmask_b32_e64 v11, v11, 0, s[48:49]
	v_exp_f32_e32 v11, v11
	v_lshlrev_b32_e32 v19, 2, v19
	v_mul_f32_e32 v2, v2, v8
	v_mul_f32_e32 v3, v3, v23
	v_add3_u32 v20, 0, v20, v19
	v_cndmask_b32_e64 v2, 0, v2, s[40:41]
	v_mul_f32_e32 v3, v3, v9
	v_mul_f32_e32 v4, v4, v23
	v_sub_u32_e32 v22, v20, v0
	v_cndmask_b32_e64 v3, v3, 0, vcc
	v_mul_f32_e32 v4, v4, v10
	v_mul_f32_e32 v5, v5, v23
	ds_write_b32 v22, v2 offset:56824
	v_sub_u32_e32 v2, v20, v30
	v_mul_f32_e32 v8, v31, v8
	v_mul_f32_e32 v9, v33, v9
	v_cndmask_b32_e64 v4, 0, v4, s[46:47]
	v_mul_f32_e32 v10, v35, v10
	v_mul_f32_e32 v5, v5, v11
	v_mul_f32_e32 v11, v28, v11
	ds_write_b32 v2, v3 offset:56824
	v_sub_u32_e32 v2, v20, v37
	v_cndmask_b32_e64 v8, v8, 0, vcc
	v_cndmask_b32_e64 v9, v9, 0, s[42:43]
	v_cndmask_b32_e64 v10, v10, 0, s[44:45]
	v_cndmask_b32_e64 v5, 0, v5, s[50:51]
	v_cndmask_b32_e64 v11, v11, 0, s[48:49]
	ds_write_b32 v2, v4 offset:56824
	v_sub_u32_e32 v2, v20, v38
	ds_write_b32 v2, v5 offset:56824
	v_cvt_pk_bf16_f32 v2, v8, v9
	v_cvt_pk_bf16_f32 v3, v10, v11
	s_or_b32 s1, s1, 1
	ds_write_b64 v26, v[2:3] offset:9216
	s_mul_i32 s3, s1, 0x900
	v_add_u32_e32 v14, s3, v14
	ds_read_b128 v[8:11], v12 offset:9216
	ds_read_b128 v[2:5], v14 offset:9216
	ds_read_b128 v[22:25], v12 offset:9280
	ds_read_b128 v[26:29], v14 offset:9280
	s_waitcnt lgkmcnt(2)
;     ...
;     for (int k2 = 0; k2 < 2; ++k2) {
;         const int tt = 2 * w + k2, mt = tt >> 2, nt = tt & 3;
;         f32x4 accG = {0.f, 0.f, 0.f, 0.f}, accQ = {0.f, 0.f, 0.f, 0.f};
;         accG = mma_ll<2>(Ks + mt * 16 * 72, 72, Ks + nt * 16 * 72, 72, accG, lane);
;         accQ = mma_ll<2>(Ks + mt * 16 * 72, 72, Qs + nt * 16 * 72, 72, accQ, lane);
;         const int n = nt * 16 + lr, m0 = mt * 16 + 4 * lq;
; #pragma unroll
;         for (int d = 0; d < 2; ++d) {
;             const float gcn = gcS[d * 64 + n], bn = bS[d * 64 + n];
;             f32x4 av, tv;
; #pragma unroll
;             for (int i = 0; i < 4; ++i) { const int m = m0 + i; const float gcm = gcS[d * 64 + m];
;                 const bool strict = d == 0 ? (m < n) : (m > n); const bool incl = d == 0 ? (m <= n) : (m >= n);
;                 const float e = fexp(incl ? (gcn - gcm) : 0.f);
;                 av[i] = strict ? bn * accG[i] * e : 0.f; tv[i] = incl ? 0.125f * accQ[i] * e : 0.f; }
; #pragma unroll
;             for (int i = 0; i < 4; ++i) { const int si = d ? 63 - n : n, sj = d ? 63 - (m0 + i) : m0 + i; As[d * 4352 + (si >> 1) * 136 + sj * 2 + (si & 1)] = av[i]; }
;             *(LAS v2u*)(At + d * 4608 + n * 72 + m0) = pack4(tv);
;         }
;     }
;     ...
;     if (w < 2) {
;         const int d = w; const LAS float* Ad = As + d * 4352;
;         float tr[64]; int lane_o = lane;
; #pragma unroll
;         for (int ip = 0; ip < 32; ++ip) {
;             const int i0 = 2 * ip;
;             f32x4 rv[32];
; #pragma unroll
;             for (int jp = 0; jp <= ip; ++jp) rv[jp] = *(const LAS f32x4*)(Ad + ip * 136 + 4 * jp);
;             asm volatile("" : "+v"(lane_o) :: "memory");
;             f32x2_ a0 = {0.f, 0.f}, a1 = {0.f, 0.f}, a2 = {0.f, 0.f}, a3 = {0.f, 0.f};
; #pragma unroll
;             for (int jp = 0; jp < ip; ++jp) {
;                 const f32x2_ ta = {tr[2 * jp], tr[2 * jp]}, tb = {tr[2 * jp + 1], tr[2 * jp + 1]};
;                 const f32x2_ va = {rv[jp][0], rv[jp][1]}, vb = {rv[jp][2], rv[jp][3]};
;                 if (jp & 1) { a2 += va * ta; a3 += vb * tb; } else { a0 += va * ta; a1 += vb * tb; }
;             }
;             const f32x2_ sum = (a0 + a1) + (a2 + a3);
;             const float t0 = (lane_o == i0 ? 1.f : 0.f) - sum[0];
;             tr[i0] = t0;
;             tr[i0 + 1] = (lane_o == i0 + 1 ? 1.f : 0.f) - sum[1] - rv[ip][1] * t0;
;         }
	v_mfma_f32_16x16x32_bf16 v[2:5], v[8:11], v[2:5], 0
	v_lshl_or_b32 v12, s1, 4, v109
	v_cmp_lt_i32_e32 vcc, v15, v12
	v_cmp_gt_i32_e64 s[40:41], v15, v12
	s_waitcnt lgkmcnt(0)
	v_mfma_f32_16x16x32_bf16 v[2:5], v[22:25], v[26:29], v[2:5]
	ds_read_b128 v[26:29], v14
	v_cmp_gt_i32_e64 s[46:47], v34, v12
	v_cmp_gt_i32_e64 s[50:51], v36, v12
	s_waitcnt lgkmcnt(0)
	v_mfma_f32_16x16x32_bf16 v[8:11], v[8:11], v[26:29], 0
	ds_read_b128 v[26:29], v14 offset:64
	v_mad_u32_u24 v14, v12, s4, v16
	v_lshl_add_u32 v16, v12, 2, 0
	s_waitcnt lgkmcnt(0)
	v_mfma_f32_16x16x32_bf16 v[8:11], v[22:25], v[26:29], v[8:11]
	ds_read_b32 v20, v16 offset:37888
	ds_read_b32 v26, v16 offset:37376
	ds_read_b128 v[22:25], v6 offset:37888
	v_cmp_lt_i32_e64 s[42:43], v32, v12
	v_cmp_lt_i32_e64 s[44:45], v34, v12
	s_nop 2
	v_mul_f32_e32 v27, 0x3e000000, v8
	v_mul_f32_e32 v28, 0x3e000000, v9
	s_waitcnt lgkmcnt(0)
	v_sub_f32_e32 v15, v20, v22
	v_mul_f32_e32 v15, 0x3fb8aa3b, v15
	v_cndmask_b32_e64 v15, v15, 0, s[40:41]
	v_exp_f32_e32 v15, v15
	v_mul_f32_e32 v22, v2, v26
	v_mul_f32_e32 v29, 0x3e000000, v10
	v_cmp_lt_i32_e64 s[48:49], v36, v12
	v_mul_f32_e32 v22, v22, v15
	v_mul_f32_e32 v8, v27, v15
	v_sub_f32_e32 v15, v20, v23
	v_mul_f32_e32 v15, 0x3fb8aa3b, v15
	v_cndmask_b32_e32 v15, 0, v15, vcc
	v_exp_f32_e32 v15, v15
	v_mul_f32_e32 v23, v3, v26
	v_lshrrev_b32_e32 v12, 1, v12
	v_cndmask_b32_e32 v22, 0, v22, vcc
	v_mul_f32_e32 v23, v23, v15
	v_mul_f32_e32 v9, v28, v15
	v_sub_f32_e32 v15, v20, v24
	v_mul_f32_e32 v15, 0x3fb8aa3b, v15
	v_cndmask_b32_e64 v15, v15, 0, s[46:47]
	v_exp_f32_e32 v15, v15
	v_mul_f32_e32 v24, v4, v26
	v_cndmask_b32_e64 v8, v8, 0, s[40:41]
	v_cndmask_b32_e64 v23, 0, v23, s[42:43]
	v_mul_f32_e32 v24, v24, v15
	v_mul_f32_e32 v10, v29, v15
	v_sub_f32_e32 v15, v20, v25
	v_mul_f32_e32 v15, 0x3fb8aa3b, v15
	v_cndmask_b32_e64 v15, v15, 0, s[50:51]
	v_exp_f32_e32 v15, v15
	v_mul_f32_e32 v20, v5, v26
	v_mul_f32_e32 v25, 0x3e000000, v11
	v_cndmask_b32_e32 v9, 0, v9, vcc
	v_mul_f32_e32 v20, v20, v15
	v_mul_f32_e32 v11, v25, v15
	v_mul_u32_u24_e32 v15, 0x220, v12
	v_add3_u32 v15, 0, v15, v18
	v_add_u32_e32 v18, v15, v0
	v_cndmask_b32_e64 v10, v10, 0, s[46:47]
	v_cndmask_b32_e64 v11, v11, 0, s[50:51]
	ds_write_b32 v18, v22 offset:38912
	v_add_u32_e32 v18, v15, v30
	v_cndmask_b32_e64 v24, 0, v24, s[44:45]
	v_cndmask_b32_e64 v20, 0, v20, s[48:49]
	ds_write_b32 v18, v23 offset:38912
	v_add_u32_e32 v18, v15, v37
	v_add_u32_e32 v15, v15, v38
	v_cvt_pk_bf16_f32 v8, v8, v9
	v_cvt_pk_bf16_f32 v9, v10, v11
	ds_write_b32 v18, v24 offset:38912
	ds_write_b32 v15, v20 offset:38912
	ds_write_b64 v14, v[8:9]
	ds_read_b32 v15, v16 offset:38144
	ds_read_b32 v16, v16 offset:37632
	ds_read_b128 v[8:11], v6 offset:38144
	s_movk_i32 s92, 0x90
	s_waitcnt lgkmcnt(1)
	v_mul_f32_e32 v2, v2, v16
	s_waitcnt lgkmcnt(0)
	v_sub_f32_e32 v6, v15, v8
	v_mul_f32_e32 v6, 0x3fb8aa3b, v6
	v_sub_f32_e32 v8, v15, v9
	v_cndmask_b32_e64 v6, v6, 0, vcc
	v_mul_f32_e32 v8, 0x3fb8aa3b, v8
	v_sub_f32_e32 v9, v15, v10
	v_sub_f32_e32 v10, v15, v11
	v_exp_f32_e32 v6, v6
	v_cndmask_b32_e64 v8, v8, 0, s[42:43]
	v_mul_f32_e32 v9, 0x3fb8aa3b, v9
	v_mul_f32_e32 v10, 0x3fb8aa3b, v10
	v_exp_f32_e32 v8, v8
	v_cndmask_b32_e64 v9, v9, 0, s[44:45]
	v_cndmask_b32_e64 v10, v10, 0, s[48:49]
	v_exp_f32_e32 v9, v9
	v_exp_f32_e32 v10, v10
	v_xor_b32_e32 v11, 31, v12
	v_mul_u32_u24_e32 v11, 0x220, v11
	v_mul_f32_e32 v2, v2, v6
	v_mul_f32_e32 v3, v3, v16
	v_add3_u32 v11, 0, v11, v19
	v_cndmask_b32_e64 v2, 0, v2, s[40:41]
	v_mul_f32_e32 v3, v3, v8
	v_mul_f32_e32 v4, v4, v16
	v_mul_f32_e32 v5, v5, v16
	v_sub_u32_e32 v0, v11, v0
	v_mul_f32_e32 v6, v27, v6
	v_cndmask_b32_e64 v3, v3, 0, vcc
	v_mul_f32_e32 v8, v28, v8
	v_mul_f32_e32 v4, v4, v9
	v_mul_f32_e32 v9, v29, v9
	v_mul_f32_e32 v5, v5, v10
	v_mul_f32_e32 v10, v25, v10
	ds_write_b32 v0, v2 offset:56824
	v_sub_u32_e32 v0, v11, v30
	v_cndmask_b32_e64 v6, v6, 0, vcc
	v_cndmask_b32_e64 v8, v8, 0, s[42:43]
	v_cndmask_b32_e64 v4, 0, v4, s[46:47]
	v_cndmask_b32_e64 v9, v9, 0, s[44:45]
	v_cndmask_b32_e64 v10, v10, 0, s[48:49]
	ds_write_b32 v0, v3 offset:56824
	v_sub_u32_e32 v0, v11, v37
	v_cndmask_b32_e64 v5, 0, v5, s[50:51]
	ds_write_b32 v0, v4 offset:56824
	v_sub_u32_e32 v0, v11, v38
	v_cvt_pk_bf16_f32 v2, v6, v8
	v_cvt_pk_bf16_f32 v3, v9, v10
	s_andn2_b64 vcc, exec, s[10:11]
	ds_write_b32 v0, v5 offset:56824
	ds_write_b64 v14, v[2:3] offset:9216
	s_waitcnt lgkmcnt(0)
	s_barrier
	s_waitcnt vmcnt(0) lgkmcnt(0)
	v_mbcnt_lo_u32_b32 v0, -1, 0
	v_mbcnt_hi_u32_b32 v0, -1, v0
	s_and_b32 s1, s28, 1
	s_lshr_b32 s3, s28, 1
	s_mov_b32 s4, 0x11111111
	s_mov_b32 s5, 0x11111111
	s_mov_b32 s6, 0x22222222
	s_mov_b32 s7, 0x22222222
	s_mov_b32 s8, 0x44444444
	s_mov_b32 s9, 0x44444444
	s_mov_b32 s10, 0x88888888
	s_mov_b32 s11, 0x88888888
	v_and_b32_e32 v6, 3, v0
	v_lshrrev_b32_e32 v12, 2, v0
	s_lshl_b32 s29, s3, 4
	v_add_u32_e32 v12, s29, v12
	s_mul_i32 s29, s1, 0x4400
	s_add_i32 s29, s29, 0x9800
	v_lshlrev_b32_e32 v14, 4, v6
	v_add_u32_e32 v14, s29, v14
	s_mul_i32 s29, s1, 0x3f
	v_xor_b32_e32 v16, s29, v12
	s_lshl_b32 s29, s1, 8
	s_add_i32 s29, s29, 0x9200
	v_lshl_add_u32 v223, v16, 2, s29
	ds_read_b32 v56, v223
	ds_read_b32 v224, v223 offset:512
	s_mul_i32 s29, s1, 0x3
	v_xor_b32_e32 v223, s29, v6
	v_mul_u32_u24_e32 v223, 0x120, v223
	v_lshl_add_u32 v64, v16, 1, v223
	s_mul_i32 s29, s1, 0x4800
	s_add_i32 s29, s29, 0x12800
	v_add_u32_e32 v64, s29, v64
	v_mov_b32_e32 v2, 0
	v_mov_b32_e32 v3, 0
	v_mov_b32_e32 v4, 0
	v_mov_b32_e32 v5, 0
	v_mov_b32_e32 v8, 0
	v_mov_b32_e32 v9, 0
	v_mov_b32_e32 v10, 0
	v_mov_b32_e32 v11, 0
	v_mov_b32_e32 v18, 0
	v_mov_b32_e32 v19, 0
	v_mov_b32_e32 v50, 0
	v_mov_b32_e32 v51, 0
	v_mov_b32_e32 v54, 0
	v_mov_b32_e32 v55, 0
	v_mov_b32_e32 v58, 0
	v_mov_b32_e32 v59, 0
	s_waitcnt lgkmcnt(0)
	v_mul_f32_e32 v224, 0x3fb8aa3b, v224
	v_exp_f32_e32 v224, v224
	s_nop 0
	v_mul_f32_e32 v60, v56, v224
	s_cmp_eq_u32 s3, 0
	s_cbranch_scc1 .Lfs_ent0
	s_cmp_eq_u32 s3, 1
	s_cbranch_scc1 .Lfs_ent1
	s_cmp_eq_u32 s3, 2
	s_cbranch_scc1 .Lfs_ent2
	s_branch .Lfs_ent3
; #define LAS __attribute__((address_space(3)))
;     ...
; #pragma unroll
;         for (int ip = 0; ip < 32; ++ip) {
;             const int i0 = 2 * ip;
;             f32x4 rv[32];
; #pragma unroll
;             for (int jp = 0; jp <= ip; ++jp) rv[jp] = *(const LAS f32x4*)(Ad + ip * 136 + 4 * jp);
;             asm volatile("" : "+v"(lane_o) :: "memory");
;             f32x2_ a0 = {0.f, 0.f}, a1 = {0.f, 0.f}, a2 = {0.f, 0.f}, a3 = {0.f, 0.f};
; #pragma unroll
;             for (int jp = 0; jp < ip; ++jp) {
;                 const f32x2_ ta = {tr[2 * jp], tr[2 * jp]}, tb = {tr[2 * jp + 1], tr[2 * jp + 1]};
;                 const f32x2_ va = {rv[jp][0], rv[jp][1]}, vb = {rv[jp][2], rv[jp][3]};
;                 if (jp & 1) { a2 += va * ta; a3 += vb * tb; } else { a0 += va * ta; a1 += vb * tb; }
;             }
;             const f32x2_ sum = (a0 + a1) + (a2 + a3);
;             const float t0 = (lane_o == i0 ? 1.f : 0.f) - sum[0];
;             tr[i0] = t0;
;             tr[i0 + 1] = (lane_o == i0 + 1 ? 1.f : 0.f) - sum[1] - rv[ip][1] * t0;
;         }
.Lfs_ent0:
	ds_read_b128 v[70:73], v14 offset:0
	s_branch .Lfs_row0
.Lfs_ent1:
	ds_read_b128 v[70:73], v14 offset:4352
	ds_read_b128 v[74:77], v14 offset:4416
	ds_read_b128 v[78:81], v14 offset:4480
	s_branch .Lfs_row8
.Lfs_ent2:
	ds_read_b128 v[70:73], v14 offset:8704
	ds_read_b128 v[74:77], v14 offset:8768
	ds_read_b128 v[78:81], v14 offset:8832
	ds_read_b128 v[82:85], v14 offset:8896
	ds_read_b128 v[86:89], v14 offset:8960
	s_branch .Lfs_row16
.Lfs_ent3:
	ds_read_b128 v[70:73], v14 offset:13056
	ds_read_b128 v[74:77], v14 offset:13120
	ds_read_b128 v[78:81], v14 offset:13184
	ds_read_b128 v[82:85], v14 offset:13248
	ds_read_b128 v[86:89], v14 offset:13312
	ds_read_b128 v[90:93], v14 offset:13376
	ds_read_b128 v[94:97], v14 offset:13440
	s_branch .Lfs_row24
.Lfs_row0:
	ds_read_b128 v[122:125], v14 offset:544
	v_cmp_eq_u32_e64 s[12:13], 0, v12
	v_cmp_eq_u32_e64 s[14:15], 1, v12
	s_waitcnt lgkmcnt(1)
	v_pk_fma_f32 v[62:63], v[70:71], v[2:3], 0 op_sel_hi:[1,0,0]
	v_pk_fma_f32 v[66:67], v[72:73], v[2:3], 0 op_sel:[0,1,0] op_sel_hi:[1,1,0]
	v_cndmask_b32_e64 v68, 0, 1.0, s[12:13]
	v_cndmask_b32_e64 v112, 0, 1.0, s[14:15]
	v_pk_add_f32 v[62:63], v[62:63], v[66:67]
	s_nop 1
	v_add_f32_dpp v62, v62, v62 quad_perm:[1,0,3,2] row_mask:0xf bank_mask:0xf bound_ctrl:1
	v_add_f32_dpp v63, v63, v63 quad_perm:[1,0,3,2] row_mask:0xf bank_mask:0xf bound_ctrl:1
	s_nop 0
	v_add_f32_dpp v62, v62, v62 quad_perm:[2,3,0,1] row_mask:0xf bank_mask:0xf bound_ctrl:1
	v_add_f32_dpp v63, v63, v63 quad_perm:[2,3,0,1] row_mask:0xf bank_mask:0xf bound_ctrl:1
	v_sub_f32_e32 v116, v68, v62
	v_sub_f32_e32 v223, v112, v63
	v_fma_f32 v120, -v71, v116, v223
	v_cndmask_b32_e64 v2, v2, v116, s[4:5]
	v_cndmask_b32_e64 v3, v3, v120, s[4:5]
.Lfs_row1:
	ds_read_b128 v[70:73], v14 offset:1088
	v_cmp_eq_u32_e64 s[12:13], 2, v12
	v_cmp_eq_u32_e64 s[14:15], 3, v12
	s_waitcnt lgkmcnt(1)
	v_pk_fma_f32 v[62:63], v[122:123], v[2:3], 0 op_sel_hi:[1,0,0]
	v_pk_fma_f32 v[66:67], v[124:125], v[2:3], 0 op_sel:[0,1,0] op_sel_hi:[1,1,0]
	v_cndmask_b32_e64 v68, 0, 1.0, s[12:13]
	v_cndmask_b32_e64 v112, 0, 1.0, s[14:15]
	v_pk_add_f32 v[62:63], v[62:63], v[66:67]
	s_nop 1
	v_add_f32_dpp v62, v62, v62 quad_perm:[1,0,3,2] row_mask:0xf bank_mask:0xf bound_ctrl:1
	v_add_f32_dpp v63, v63, v63 quad_perm:[1,0,3,2] row_mask:0xf bank_mask:0xf bound_ctrl:1
	s_nop 0
	v_add_f32_dpp v62, v62, v62 quad_perm:[2,3,0,1] row_mask:0xf bank_mask:0xf bound_ctrl:1
	v_add_f32_dpp v63, v63, v63 quad_perm:[2,3,0,1] row_mask:0xf bank_mask:0xf bound_ctrl:1
	v_sub_f32_e32 v116, v68, v62
	v_sub_f32_e32 v223, v112, v63
	v_fma_f32 v120, -v123, v116, v223
	v_cndmask_b32_e64 v2, v2, v116, s[6:7]
	v_cndmask_b32_e64 v3, v3, v120, s[6:7]
.Lfs_row2:
	ds_read_b128 v[122:125], v14 offset:1632
	v_cmp_eq_u32_e64 s[12:13], 4, v12
	v_cmp_eq_u32_e64 s[14:15], 5, v12
	s_waitcnt lgkmcnt(1)
	v_pk_fma_f32 v[62:63], v[70:71], v[2:3], 0 op_sel_hi:[1,0,0]
	v_pk_fma_f32 v[66:67], v[72:73], v[2:3], 0 op_sel:[0,1,0] op_sel_hi:[1,1,0]
	v_cndmask_b32_e64 v68, 0, 1.0, s[12:13]
	v_cndmask_b32_e64 v112, 0, 1.0, s[14:15]
	v_pk_add_f32 v[62:63], v[62:63], v[66:67]
	s_nop 1
	v_add_f32_dpp v62, v62, v62 quad_perm:[1,0,3,2] row_mask:0xf bank_mask:0xf bound_ctrl:1
	v_add_f32_dpp v63, v63, v63 quad_perm:[1,0,3,2] row_mask:0xf bank_mask:0xf bound_ctrl:1
	s_nop 0
	v_add_f32_dpp v62, v62, v62 quad_perm:[2,3,0,1] row_mask:0xf bank_mask:0xf bound_ctrl:1
	v_add_f32_dpp v63, v63, v63 quad_perm:[2,3,0,1] row_mask:0xf bank_mask:0xf bound_ctrl:1
	v_sub_f32_e32 v116, v68, v62
	v_sub_f32_e32 v223, v112, v63
	v_fma_f32 v120, -v71, v116, v223
	v_cndmask_b32_e64 v2, v2, v116, s[8:9]
	v_cndmask_b32_e64 v3, v3, v120, s[8:9]
.Lfs_row3:
	ds_read_b128 v[70:73], v14 offset:2176
	ds_read_b128 v[74:77], v14 offset:2240
	v_cmp_eq_u32_e64 s[12:13], 6, v12
	v_cmp_eq_u32_e64 s[14:15], 7, v12
	s_waitcnt lgkmcnt(2)
	v_pk_fma_f32 v[62:63], v[122:123], v[2:3], 0 op_sel_hi:[1,0,0]
	v_pk_fma_f32 v[66:67], v[124:125], v[2:3], 0 op_sel:[0,1,0] op_sel_hi:[1,1,0]
	v_cndmask_b32_e64 v68, 0, 1.0, s[12:13]
	v_cndmask_b32_e64 v112, 0, 1.0, s[14:15]
	v_pk_add_f32 v[62:63], v[62:63], v[66:67]
	s_nop 1
	v_add_f32_dpp v62, v62, v62 quad_perm:[1,0,3,2] row_mask:0xf bank_mask:0xf bound_ctrl:1
	v_add_f32_dpp v63, v63, v63 quad_perm:[1,0,3,2] row_mask:0xf bank_mask:0xf bound_ctrl:1
	s_nop 0
	v_add_f32_dpp v62, v62, v62 quad_perm:[2,3,0,1] row_mask:0xf bank_mask:0xf bound_ctrl:1
	v_add_f32_dpp v63, v63, v63 quad_perm:[2,3,0,1] row_mask:0xf bank_mask:0xf bound_ctrl:1
	v_sub_f32_e32 v116, v68, v62
	v_sub_f32_e32 v223, v112, v63
	v_fma_f32 v120, -v123, v116, v223
	v_cndmask_b32_e64 v2, v2, v116, s[10:11]
	v_cndmask_b32_e64 v3, v3, v120, s[10:11]
.Lfs_row4:
	ds_read_b128 v[122:125], v14 offset:2720
	ds_read_b128 v[126:129], v14 offset:2784
	v_cmp_eq_u32_e64 s[12:13], 8, v12
	v_cmp_eq_u32_e64 s[14:15], 9, v12
	s_waitcnt lgkmcnt(2)
	v_pk_fma_f32 v[62:63], v[74:75], v[4:5], 0 op_sel_hi:[1,0,0]
	v_pk_fma_f32 v[66:67], v[76:77], v[4:5], 0 op_sel:[0,1,0] op_sel_hi:[1,1,0]
	v_cndmask_b32_e64 v68, 0, 1.0, s[12:13]
	v_cndmask_b32_e64 v112, 0, 1.0, s[14:15]
	v_pk_fma_f32 v[106:107], v[70:71], v[2:3], 0 op_sel_hi:[1,0,0]
	v_pk_fma_f32 v[110:111], v[72:73], v[2:3], 0 op_sel:[0,1,0] op_sel_hi:[1,1,0]
	v_pk_add_f32 v[62:63], v[62:63], v[106:107]
	v_pk_add_f32 v[66:67], v[66:67], v[110:111]
	v_pk_add_f32 v[62:63], v[62:63], v[66:67]
	s_nop 1
	v_add_f32_dpp v62, v62, v62 quad_perm:[1,0,3,2] row_mask:0xf bank_mask:0xf bound_ctrl:1
	v_add_f32_dpp v63, v63, v63 quad_perm:[1,0,3,2] row_mask:0xf bank_mask:0xf bound_ctrl:1
	s_nop 0
	v_add_f32_dpp v62, v62, v62 quad_perm:[2,3,0,1] row_mask:0xf bank_mask:0xf bound_ctrl:1
	v_add_f32_dpp v63, v63, v63 quad_perm:[2,3,0,1] row_mask:0xf bank_mask:0xf bound_ctrl:1
	v_sub_f32_e32 v116, v68, v62
	v_sub_f32_e32 v223, v112, v63
	v_fma_f32 v120, -v75, v116, v223
	v_cndmask_b32_e64 v4, v4, v116, s[4:5]
	v_cndmask_b32_e64 v5, v5, v120, s[4:5]
; #define LAS __attribute__((address_space(3)))
;     ...
; #pragma unroll
;         for (int ip = 0; ip < 32; ++ip) {
;             const int i0 = 2 * ip;
;             f32x4 rv[32];
; #pragma unroll
;             for (int jp = 0; jp <= ip; ++jp) rv[jp] = *(const LAS f32x4*)(Ad + ip * 136 + 4 * jp);
;             asm volatile("" : "+v"(lane_o) :: "memory");
;             f32x2_ a0 = {0.f, 0.f}, a1 = {0.f, 0.f}, a2 = {0.f, 0.f}, a3 = {0.f, 0.f};
; #pragma unroll
;             for (int jp = 0; jp < ip; ++jp) {
;                 const f32x2_ ta = {tr[2 * jp], tr[2 * jp]}, tb = {tr[2 * jp + 1], tr[2 * jp + 1]};
;                 const f32x2_ va = {rv[jp][0], rv[jp][1]}, vb = {rv[jp][2], rv[jp][3]};
;                 if (jp & 1) { a2 += va * ta; a3 += vb * tb; } else { a0 += va * ta; a1 += vb * tb; }
;             }
;             const f32x2_ sum = (a0 + a1) + (a2 + a3);
;             const float t0 = (lane_o == i0 ? 1.f : 0.f) - sum[0];
;             tr[i0] = t0;
;             tr[i0 + 1] = (lane_o == i0 + 1 ? 1.f : 0.f) - sum[1] - rv[ip][1] * t0;
;         }
.Lfs_row5:
	ds_read_b128 v[70:73], v14 offset:3264
	ds_read_b128 v[74:77], v14 offset:3328
	v_cmp_eq_u32_e64 s[12:13], 10, v12
	v_cmp_eq_u32_e64 s[14:15], 11, v12
	s_waitcnt lgkmcnt(2)
	v_pk_fma_f32 v[62:63], v[122:123], v[2:3], 0 op_sel_hi:[1,0,0]
	v_pk_fma_f32 v[66:67], v[124:125], v[2:3], 0 op_sel:[0,1,0] op_sel_hi:[1,1,0]
	v_cndmask_b32_e64 v68, 0, 1.0, s[12:13]
	v_cndmask_b32_e64 v112, 0, 1.0, s[14:15]
	v_pk_fma_f32 v[106:107], v[126:127], v[4:5], 0 op_sel_hi:[1,0,0]
	v_pk_fma_f32 v[110:111], v[128:129], v[4:5], 0 op_sel:[0,1,0] op_sel_hi:[1,1,0]
	v_pk_add_f32 v[62:63], v[62:63], v[106:107]
	v_pk_add_f32 v[66:67], v[66:67], v[110:111]
	v_pk_add_f32 v[62:63], v[62:63], v[66:67]
	s_nop 1
	v_add_f32_dpp v62, v62, v62 quad_perm:[1,0,3,2] row_mask:0xf bank_mask:0xf bound_ctrl:1
	v_add_f32_dpp v63, v63, v63 quad_perm:[1,0,3,2] row_mask:0xf bank_mask:0xf bound_ctrl:1
	s_nop 0
	v_add_f32_dpp v62, v62, v62 quad_perm:[2,3,0,1] row_mask:0xf bank_mask:0xf bound_ctrl:1
	v_add_f32_dpp v63, v63, v63 quad_perm:[2,3,0,1] row_mask:0xf bank_mask:0xf bound_ctrl:1
	v_sub_f32_e32 v116, v68, v62
	v_sub_f32_e32 v223, v112, v63
	v_fma_f32 v120, -v127, v116, v223
	v_cndmask_b32_e64 v4, v4, v116, s[6:7]
	v_cndmask_b32_e64 v5, v5, v120, s[6:7]
.Lfs_row6:
	ds_read_b128 v[122:125], v14 offset:3808
	ds_read_b128 v[126:129], v14 offset:3872
	v_cmp_eq_u32_e64 s[12:13], 12, v12
	v_cmp_eq_u32_e64 s[14:15], 13, v12
	s_waitcnt lgkmcnt(2)
	v_pk_fma_f32 v[62:63], v[70:71], v[2:3], 0 op_sel_hi:[1,0,0]
	v_pk_fma_f32 v[66:67], v[72:73], v[2:3], 0 op_sel:[0,1,0] op_sel_hi:[1,1,0]
	v_cndmask_b32_e64 v68, 0, 1.0, s[12:13]
	v_cndmask_b32_e64 v112, 0, 1.0, s[14:15]
	v_pk_fma_f32 v[106:107], v[74:75], v[4:5], 0 op_sel_hi:[1,0,0]
	v_pk_fma_f32 v[110:111], v[76:77], v[4:5], 0 op_sel:[0,1,0] op_sel_hi:[1,1,0]
	v_pk_add_f32 v[62:63], v[62:63], v[106:107]
	v_pk_add_f32 v[66:67], v[66:67], v[110:111]
	v_pk_add_f32 v[62:63], v[62:63], v[66:67]
	s_nop 1
	v_add_f32_dpp v62, v62, v62 quad_perm:[1,0,3,2] row_mask:0xf bank_mask:0xf bound_ctrl:1
	v_add_f32_dpp v63, v63, v63 quad_perm:[1,0,3,2] row_mask:0xf bank_mask:0xf bound_ctrl:1
	s_nop 0
	v_add_f32_dpp v62, v62, v62 quad_perm:[2,3,0,1] row_mask:0xf bank_mask:0xf bound_ctrl:1
	v_add_f32_dpp v63, v63, v63 quad_perm:[2,3,0,1] row_mask:0xf bank_mask:0xf bound_ctrl:1
	v_sub_f32_e32 v116, v68, v62
	v_sub_f32_e32 v223, v112, v63
	v_fma_f32 v120, -v75, v116, v223
	v_cndmask_b32_e64 v4, v4, v116, s[8:9]
	v_cndmask_b32_e64 v5, v5, v120, s[8:9]
.Lfs_row7:
	ds_read_b128 v[70:73], v14 offset:4352
	ds_read_b128 v[74:77], v14 offset:4416
	ds_read_b128 v[78:81], v14 offset:4480
	v_cmp_eq_u32_e64 s[12:13], 14, v12
	v_cmp_eq_u32_e64 s[14:15], 15, v12
	s_waitcnt lgkmcnt(3)
	v_pk_fma_f32 v[62:63], v[122:123], v[2:3], 0 op_sel_hi:[1,0,0]
	v_pk_fma_f32 v[66:67], v[124:125], v[2:3], 0 op_sel:[0,1,0] op_sel_hi:[1,1,0]
	v_cndmask_b32_e64 v68, 0, 1.0, s[12:13]
	v_cndmask_b32_e64 v112, 0, 1.0, s[14:15]
	v_pk_fma_f32 v[106:107], v[126:127], v[4:5], 0 op_sel_hi:[1,0,0]
	v_pk_fma_f32 v[110:111], v[128:129], v[4:5], 0 op_sel:[0,1,0] op_sel_hi:[1,1,0]
	v_pk_add_f32 v[62:63], v[62:63], v[106:107]
	v_pk_add_f32 v[66:67], v[66:67], v[110:111]
	v_pk_add_f32 v[62:63], v[62:63], v[66:67]
	s_nop 1
	v_add_f32_dpp v62, v62, v62 quad_perm:[1,0,3,2] row_mask:0xf bank_mask:0xf bound_ctrl:1
	v_add_f32_dpp v63, v63, v63 quad_perm:[1,0,3,2] row_mask:0xf bank_mask:0xf bound_ctrl:1
	s_nop 0
	v_add_f32_dpp v62, v62, v62 quad_perm:[2,3,0,1] row_mask:0xf bank_mask:0xf bound_ctrl:1
	v_add_f32_dpp v63, v63, v63 quad_perm:[2,3,0,1] row_mask:0xf bank_mask:0xf bound_ctrl:1
	v_sub_f32_e32 v116, v68, v62
	v_sub_f32_e32 v223, v112, v63
	v_fma_f32 v120, -v127, v116, v223
	v_cndmask_b32_e64 v4, v4, v116, s[10:11]
	v_cndmask_b32_e64 v5, v5, v120, s[10:11]
.Lfs_row8:
	ds_read_b128 v[122:125], v14 offset:4896
	ds_read_b128 v[126:129], v14 offset:4960
	ds_read_b128 v[130:133], v14 offset:5024
	v_cmp_eq_u32_e64 s[12:13], 16, v12
	v_cmp_eq_u32_e64 s[14:15], 17, v12
	s_waitcnt lgkmcnt(3)
	v_pk_fma_f32 v[62:63], v[70:71], v[2:3], 0 op_sel_hi:[1,0,0]
	v_pk_fma_f32 v[66:67], v[72:73], v[2:3], 0 op_sel:[0,1,0] op_sel_hi:[1,1,0]
	v_cndmask_b32_e64 v68, 0, 1.0, s[12:13]
	v_cndmask_b32_e64 v112, 0, 1.0, s[14:15]
	v_pk_fma_f32 v[106:107], v[78:79], v[8:9], 0 op_sel_hi:[1,0,0]
	v_pk_fma_f32 v[110:111], v[80:81], v[8:9], 0 op_sel:[0,1,0] op_sel_hi:[1,1,0]
	v_pk_fma_f32 v[62:63], v[74:75], v[4:5], v[62:63] op_sel_hi:[1,0,1]
	v_pk_fma_f32 v[66:67], v[76:77], v[4:5], v[66:67] op_sel:[0,1,0] op_sel_hi:[1,1,1]
	v_pk_add_f32 v[62:63], v[62:63], v[106:107]
	v_pk_add_f32 v[66:67], v[66:67], v[110:111]
	v_pk_add_f32 v[62:63], v[62:63], v[66:67]
	s_nop 1
	v_add_f32_dpp v62, v62, v62 quad_perm:[1,0,3,2] row_mask:0xf bank_mask:0xf bound_ctrl:1
	v_add_f32_dpp v63, v63, v63 quad_perm:[1,0,3,2] row_mask:0xf bank_mask:0xf bound_ctrl:1
	s_nop 0
	v_add_f32_dpp v62, v62, v62 quad_perm:[2,3,0,1] row_mask:0xf bank_mask:0xf bound_ctrl:1
	v_add_f32_dpp v63, v63, v63 quad_perm:[2,3,0,1] row_mask:0xf bank_mask:0xf bound_ctrl:1
	v_sub_f32_e32 v116, v68, v62
	v_sub_f32_e32 v223, v112, v63
	v_fma_f32 v120, -v79, v116, v223
	v_cndmask_b32_e64 v8, v8, v116, s[4:5]
	v_cndmask_b32_e64 v9, v9, v120, s[4:5]
; #define LAS __attribute__((address_space(3)))
;     ...
; #pragma unroll
;         for (int ip = 0; ip < 32; ++ip) {
;             const int i0 = 2 * ip;
;             f32x4 rv[32];
; #pragma unroll
;             for (int jp = 0; jp <= ip; ++jp) rv[jp] = *(const LAS f32x4*)(Ad + ip * 136 + 4 * jp);
;             asm volatile("" : "+v"(lane_o) :: "memory");
;             f32x2_ a0 = {0.f, 0.f}, a1 = {0.f, 0.f}, a2 = {0.f, 0.f}, a3 = {0.f, 0.f};
; #pragma unroll
;             for (int jp = 0; jp < ip; ++jp) {
;                 const f32x2_ ta = {tr[2 * jp], tr[2 * jp]}, tb = {tr[2 * jp + 1], tr[2 * jp + 1]};
;                 const f32x2_ va = {rv[jp][0], rv[jp][1]}, vb = {rv[jp][2], rv[jp][3]};
;                 if (jp & 1) { a2 += va * ta; a3 += vb * tb; } else { a0 += va * ta; a1 += vb * tb; }
;             }
;             const f32x2_ sum = (a0 + a1) + (a2 + a3);
;             const float t0 = (lane_o == i0 ? 1.f : 0.f) - sum[0];
;             tr[i0] = t0;
;             tr[i0 + 1] = (lane_o == i0 + 1 ? 1.f : 0.f) - sum[1] - rv[ip][1] * t0;
;         }
.Lfs_row9:
	ds_read_b128 v[70:73], v14 offset:5440
	ds_read_b128 v[74:77], v14 offset:5504
	ds_read_b128 v[78:81], v14 offset:5568
	v_cmp_eq_u32_e64 s[12:13], 18, v12
	v_cmp_eq_u32_e64 s[14:15], 19, v12
	s_waitcnt lgkmcnt(3)
	v_pk_fma_f32 v[62:63], v[122:123], v[2:3], 0 op_sel_hi:[1,0,0]
	v_pk_fma_f32 v[66:67], v[124:125], v[2:3], 0 op_sel:[0,1,0] op_sel_hi:[1,1,0]
	v_cndmask_b32_e64 v68, 0, 1.0, s[12:13]
	v_cndmask_b32_e64 v112, 0, 1.0, s[14:15]
	v_pk_fma_f32 v[106:107], v[126:127], v[4:5], 0 op_sel_hi:[1,0,0]
	v_pk_fma_f32 v[110:111], v[128:129], v[4:5], 0 op_sel:[0,1,0] op_sel_hi:[1,1,0]
	v_pk_fma_f32 v[62:63], v[130:131], v[8:9], v[62:63] op_sel_hi:[1,0,1]
	v_pk_fma_f32 v[66:67], v[132:133], v[8:9], v[66:67] op_sel:[0,1,0] op_sel_hi:[1,1,1]
	v_pk_add_f32 v[62:63], v[62:63], v[106:107]
	v_pk_add_f32 v[66:67], v[66:67], v[110:111]
	v_pk_add_f32 v[62:63], v[62:63], v[66:67]
	s_nop 1
	v_add_f32_dpp v62, v62, v62 quad_perm:[1,0,3,2] row_mask:0xf bank_mask:0xf bound_ctrl:1
	v_add_f32_dpp v63, v63, v63 quad_perm:[1,0,3,2] row_mask:0xf bank_mask:0xf bound_ctrl:1
	s_nop 0
	v_add_f32_dpp v62, v62, v62 quad_perm:[2,3,0,1] row_mask:0xf bank_mask:0xf bound_ctrl:1
	v_add_f32_dpp v63, v63, v63 quad_perm:[2,3,0,1] row_mask:0xf bank_mask:0xf bound_ctrl:1
	v_sub_f32_e32 v116, v68, v62
	v_sub_f32_e32 v223, v112, v63
	v_fma_f32 v120, -v131, v116, v223
	v_cndmask_b32_e64 v8, v8, v116, s[6:7]
	v_cndmask_b32_e64 v9, v9, v120, s[6:7]
.Lfs_row10:
	ds_read_b128 v[122:125], v14 offset:5984
	ds_read_b128 v[126:129], v14 offset:6048
	ds_read_b128 v[130:133], v14 offset:6112
	v_cmp_eq_u32_e64 s[12:13], 20, v12
	v_cmp_eq_u32_e64 s[14:15], 21, v12
	s_waitcnt lgkmcnt(3)
	v_pk_fma_f32 v[62:63], v[70:71], v[2:3], 0 op_sel_hi:[1,0,0]
	v_pk_fma_f32 v[66:67], v[72:73], v[2:3], 0 op_sel:[0,1,0] op_sel_hi:[1,1,0]
	v_cndmask_b32_e64 v68, 0, 1.0, s[12:13]
	v_cndmask_b32_e64 v112, 0, 1.0, s[14:15]
	v_pk_fma_f32 v[106:107], v[74:75], v[4:5], 0 op_sel_hi:[1,0,0]
	v_pk_fma_f32 v[110:111], v[76:77], v[4:5], 0 op_sel:[0,1,0] op_sel_hi:[1,1,0]
	v_pk_fma_f32 v[62:63], v[78:79], v[8:9], v[62:63] op_sel_hi:[1,0,1]
	v_pk_fma_f32 v[66:67], v[80:81], v[8:9], v[66:67] op_sel:[0,1,0] op_sel_hi:[1,1,1]
	v_pk_add_f32 v[62:63], v[62:63], v[106:107]
	v_pk_add_f32 v[66:67], v[66:67], v[110:111]
	v_pk_add_f32 v[62:63], v[62:63], v[66:67]
	s_nop 1
	v_add_f32_dpp v62, v62, v62 quad_perm:[1,0,3,2] row_mask:0xf bank_mask:0xf bound_ctrl:1
	v_add_f32_dpp v63, v63, v63 quad_perm:[1,0,3,2] row_mask:0xf bank_mask:0xf bound_ctrl:1
	s_nop 0
	v_add_f32_dpp v62, v62, v62 quad_perm:[2,3,0,1] row_mask:0xf bank_mask:0xf bound_ctrl:1
	v_add_f32_dpp v63, v63, v63 quad_perm:[2,3,0,1] row_mask:0xf bank_mask:0xf bound_ctrl:1
	v_sub_f32_e32 v116, v68, v62
	v_sub_f32_e32 v223, v112, v63
	v_fma_f32 v120, -v79, v116, v223
	v_cndmask_b32_e64 v8, v8, v116, s[8:9]
	v_cndmask_b32_e64 v9, v9, v120, s[8:9]
.Lfs_row11:
	ds_read_b128 v[70:73], v14 offset:6528
	ds_read_b128 v[74:77], v14 offset:6592
	ds_read_b128 v[78:81], v14 offset:6656
	ds_read_b128 v[82:85], v14 offset:6720
	v_cmp_eq_u32_e64 s[12:13], 22, v12
	v_cmp_eq_u32_e64 s[14:15], 23, v12
	s_waitcnt lgkmcnt(4)
	v_pk_fma_f32 v[62:63], v[122:123], v[2:3], 0 op_sel_hi:[1,0,0]
	v_pk_fma_f32 v[66:67], v[124:125], v[2:3], 0 op_sel:[0,1,0] op_sel_hi:[1,1,0]
	v_cndmask_b32_e64 v68, 0, 1.0, s[12:13]
	v_cndmask_b32_e64 v112, 0, 1.0, s[14:15]
	v_pk_fma_f32 v[106:107], v[126:127], v[4:5], 0 op_sel_hi:[1,0,0]
	v_pk_fma_f32 v[110:111], v[128:129], v[4:5], 0 op_sel:[0,1,0] op_sel_hi:[1,1,0]
	v_pk_fma_f32 v[62:63], v[130:131], v[8:9], v[62:63] op_sel_hi:[1,0,1]
	v_pk_fma_f32 v[66:67], v[132:133], v[8:9], v[66:67] op_sel:[0,1,0] op_sel_hi:[1,1,1]
	v_pk_add_f32 v[62:63], v[62:63], v[106:107]
	v_pk_add_f32 v[66:67], v[66:67], v[110:111]
	v_pk_add_f32 v[62:63], v[62:63], v[66:67]
	s_nop 1
	v_add_f32_dpp v62, v62, v62 quad_perm:[1,0,3,2] row_mask:0xf bank_mask:0xf bound_ctrl:1
	v_add_f32_dpp v63, v63, v63 quad_perm:[1,0,3,2] row_mask:0xf bank_mask:0xf bound_ctrl:1
	s_nop 0
	v_add_f32_dpp v62, v62, v62 quad_perm:[2,3,0,1] row_mask:0xf bank_mask:0xf bound_ctrl:1
	v_add_f32_dpp v63, v63, v63 quad_perm:[2,3,0,1] row_mask:0xf bank_mask:0xf bound_ctrl:1
	v_sub_f32_e32 v116, v68, v62
	v_sub_f32_e32 v223, v112, v63
	v_fma_f32 v120, -v131, v116, v223
	v_cndmask_b32_e64 v8, v8, v116, s[10:11]
	v_cndmask_b32_e64 v9, v9, v120, s[10:11]
.Lfs_row12:
	ds_read_b128 v[122:125], v14 offset:7072
	ds_read_b128 v[126:129], v14 offset:7136
	ds_read_b128 v[130:133], v14 offset:7200
	ds_read_b128 v[38:41], v14 offset:7264
	v_cmp_eq_u32_e64 s[12:13], 24, v12
	v_cmp_eq_u32_e64 s[14:15], 25, v12
	s_waitcnt lgkmcnt(4)
	v_pk_fma_f32 v[62:63], v[70:71], v[2:3], 0 op_sel_hi:[1,0,0]
	v_pk_fma_f32 v[66:67], v[72:73], v[2:3], 0 op_sel:[0,1,0] op_sel_hi:[1,1,0]
	v_cndmask_b32_e64 v68, 0, 1.0, s[12:13]
	v_cndmask_b32_e64 v112, 0, 1.0, s[14:15]
	v_pk_fma_f32 v[106:107], v[74:75], v[4:5], 0 op_sel_hi:[1,0,0]
	v_pk_fma_f32 v[110:111], v[76:77], v[4:5], 0 op_sel:[0,1,0] op_sel_hi:[1,1,0]
	v_pk_fma_f32 v[62:63], v[82:83], v[10:11], v[62:63] op_sel_hi:[1,0,1]
	v_pk_fma_f32 v[66:67], v[84:85], v[10:11], v[66:67] op_sel:[0,1,0] op_sel_hi:[1,1,1]
	v_pk_fma_f32 v[106:107], v[78:79], v[8:9], v[106:107] op_sel_hi:[1,0,1]
	v_pk_fma_f32 v[110:111], v[80:81], v[8:9], v[110:111] op_sel:[0,1,0] op_sel_hi:[1,1,1]
	v_pk_add_f32 v[62:63], v[62:63], v[106:107]
	v_pk_add_f32 v[66:67], v[66:67], v[110:111]
	v_pk_add_f32 v[62:63], v[62:63], v[66:67]
	s_nop 1
	v_add_f32_dpp v62, v62, v62 quad_perm:[1,0,3,2] row_mask:0xf bank_mask:0xf bound_ctrl:1
	v_add_f32_dpp v63, v63, v63 quad_perm:[1,0,3,2] row_mask:0xf bank_mask:0xf bound_ctrl:1
	s_nop 0
	v_add_f32_dpp v62, v62, v62 quad_perm:[2,3,0,1] row_mask:0xf bank_mask:0xf bound_ctrl:1
	v_add_f32_dpp v63, v63, v63 quad_perm:[2,3,0,1] row_mask:0xf bank_mask:0xf bound_ctrl:1
	v_sub_f32_e32 v116, v68, v62
	v_sub_f32_e32 v223, v112, v63
	v_fma_f32 v120, -v83, v116, v223
	v_cndmask_b32_e64 v10, v10, v116, s[4:5]
	v_cndmask_b32_e64 v11, v11, v120, s[4:5]
; #define LAS __attribute__((address_space(3)))
;     ...
; #pragma unroll
;         for (int ip = 0; ip < 32; ++ip) {
;             const int i0 = 2 * ip;
;             f32x4 rv[32];
; #pragma unroll
;             for (int jp = 0; jp <= ip; ++jp) rv[jp] = *(const LAS f32x4*)(Ad + ip * 136 + 4 * jp);
;             asm volatile("" : "+v"(lane_o) :: "memory");
;             f32x2_ a0 = {0.f, 0.f}, a1 = {0.f, 0.f}, a2 = {0.f, 0.f}, a3 = {0.f, 0.f};
; #pragma unroll
;             for (int jp = 0; jp < ip; ++jp) {
;                 const f32x2_ ta = {tr[2 * jp], tr[2 * jp]}, tb = {tr[2 * jp + 1], tr[2 * jp + 1]};
;                 const f32x2_ va = {rv[jp][0], rv[jp][1]}, vb = {rv[jp][2], rv[jp][3]};
;                 if (jp & 1) { a2 += va * ta; a3 += vb * tb; } else { a0 += va * ta; a1 += vb * tb; }
;             }
;             const f32x2_ sum = (a0 + a1) + (a2 + a3);
;             const float t0 = (lane_o == i0 ? 1.f : 0.f) - sum[0];
;             tr[i0] = t0;
;             tr[i0 + 1] = (lane_o == i0 + 1 ? 1.f : 0.f) - sum[1] - rv[ip][1] * t0;
;         }
.Lfs_row13:
	ds_read_b128 v[70:73], v14 offset:7616
	ds_read_b128 v[74:77], v14 offset:7680
	ds_read_b128 v[78:81], v14 offset:7744
	ds_read_b128 v[82:85], v14 offset:7808
	v_cmp_eq_u32_e64 s[12:13], 26, v12
	v_cmp_eq_u32_e64 s[14:15], 27, v12
	s_waitcnt lgkmcnt(4)
	v_pk_fma_f32 v[62:63], v[122:123], v[2:3], 0 op_sel_hi:[1,0,0]
	v_pk_fma_f32 v[66:67], v[124:125], v[2:3], 0 op_sel:[0,1,0] op_sel_hi:[1,1,0]
	v_cndmask_b32_e64 v68, 0, 1.0, s[12:13]
	v_cndmask_b32_e64 v112, 0, 1.0, s[14:15]
	v_pk_fma_f32 v[106:107], v[126:127], v[4:5], 0 op_sel_hi:[1,0,0]
	v_pk_fma_f32 v[110:111], v[128:129], v[4:5], 0 op_sel:[0,1,0] op_sel_hi:[1,1,0]
	v_pk_fma_f32 v[62:63], v[130:131], v[8:9], v[62:63] op_sel_hi:[1,0,1]
	v_pk_fma_f32 v[66:67], v[132:133], v[8:9], v[66:67] op_sel:[0,1,0] op_sel_hi:[1,1,1]
	v_pk_fma_f32 v[106:107], v[38:39], v[10:11], v[106:107] op_sel_hi:[1,0,1]
	v_pk_fma_f32 v[110:111], v[40:41], v[10:11], v[110:111] op_sel:[0,1,0] op_sel_hi:[1,1,1]
	v_pk_add_f32 v[62:63], v[62:63], v[106:107]
	v_pk_add_f32 v[66:67], v[66:67], v[110:111]
	v_pk_add_f32 v[62:63], v[62:63], v[66:67]
	s_nop 1
	v_add_f32_dpp v62, v62, v62 quad_perm:[1,0,3,2] row_mask:0xf bank_mask:0xf bound_ctrl:1
	v_add_f32_dpp v63, v63, v63 quad_perm:[1,0,3,2] row_mask:0xf bank_mask:0xf bound_ctrl:1
	s_nop 0
	v_add_f32_dpp v62, v62, v62 quad_perm:[2,3,0,1] row_mask:0xf bank_mask:0xf bound_ctrl:1
	v_add_f32_dpp v63, v63, v63 quad_perm:[2,3,0,1] row_mask:0xf bank_mask:0xf bound_ctrl:1
	v_sub_f32_e32 v116, v68, v62
	v_sub_f32_e32 v223, v112, v63
	v_fma_f32 v120, -v39, v116, v223
	v_cndmask_b32_e64 v10, v10, v116, s[6:7]
	v_cndmask_b32_e64 v11, v11, v120, s[6:7]
.Lfs_row14:
	ds_read_b128 v[122:125], v14 offset:8160
	ds_read_b128 v[126:129], v14 offset:8224
	ds_read_b128 v[130:133], v14 offset:8288
	ds_read_b128 v[38:41], v14 offset:8352
	v_cmp_eq_u32_e64 s[12:13], 28, v12
	v_cmp_eq_u32_e64 s[14:15], 29, v12
	s_waitcnt lgkmcnt(4)
	v_pk_fma_f32 v[62:63], v[70:71], v[2:3], 0 op_sel_hi:[1,0,0]
	v_pk_fma_f32 v[66:67], v[72:73], v[2:3], 0 op_sel:[0,1,0] op_sel_hi:[1,1,0]
	v_cndmask_b32_e64 v68, 0, 1.0, s[12:13]
	v_cndmask_b32_e64 v112, 0, 1.0, s[14:15]
	v_pk_fma_f32 v[106:107], v[74:75], v[4:5], 0 op_sel_hi:[1,0,0]
	v_pk_fma_f32 v[110:111], v[76:77], v[4:5], 0 op_sel:[0,1,0] op_sel_hi:[1,1,0]
	v_pk_fma_f32 v[62:63], v[78:79], v[8:9], v[62:63] op_sel_hi:[1,0,1]
	v_pk_fma_f32 v[66:67], v[80:81], v[8:9], v[66:67] op_sel:[0,1,0] op_sel_hi:[1,1,1]
	v_pk_fma_f32 v[106:107], v[82:83], v[10:11], v[106:107] op_sel_hi:[1,0,1]
	v_pk_fma_f32 v[110:111], v[84:85], v[10:11], v[110:111] op_sel:[0,1,0] op_sel_hi:[1,1,1]
	v_pk_add_f32 v[62:63], v[62:63], v[106:107]
	v_pk_add_f32 v[66:67], v[66:67], v[110:111]
	v_pk_add_f32 v[62:63], v[62:63], v[66:67]
	s_nop 1
	v_add_f32_dpp v62, v62, v62 quad_perm:[1,0,3,2] row_mask:0xf bank_mask:0xf bound_ctrl:1
	v_add_f32_dpp v63, v63, v63 quad_perm:[1,0,3,2] row_mask:0xf bank_mask:0xf bound_ctrl:1
	s_nop 0
	v_add_f32_dpp v62, v62, v62 quad_perm:[2,3,0,1] row_mask:0xf bank_mask:0xf bound_ctrl:1
	v_add_f32_dpp v63, v63, v63 quad_perm:[2,3,0,1] row_mask:0xf bank_mask:0xf bound_ctrl:1
	v_sub_f32_e32 v116, v68, v62
	v_sub_f32_e32 v223, v112, v63
	v_fma_f32 v120, -v83, v116, v223
	v_cndmask_b32_e64 v10, v10, v116, s[8:9]
	v_cndmask_b32_e64 v11, v11, v120, s[8:9]
.Lfs_row15:
	ds_read_b128 v[70:73], v14 offset:8704
	ds_read_b128 v[74:77], v14 offset:8768
	ds_read_b128 v[78:81], v14 offset:8832
	ds_read_b128 v[82:85], v14 offset:8896
	ds_read_b128 v[86:89], v14 offset:8960
	v_cmp_eq_u32_e64 s[12:13], 30, v12
	v_cmp_eq_u32_e64 s[14:15], 31, v12
	s_waitcnt lgkmcnt(5)
	v_pk_fma_f32 v[62:63], v[122:123], v[2:3], 0 op_sel_hi:[1,0,0]
	v_pk_fma_f32 v[66:67], v[124:125], v[2:3], 0 op_sel:[0,1,0] op_sel_hi:[1,1,0]
	v_cndmask_b32_e64 v68, 0, 1.0, s[12:13]
	v_cndmask_b32_e64 v112, 0, 1.0, s[14:15]
	v_pk_fma_f32 v[106:107], v[126:127], v[4:5], 0 op_sel_hi:[1,0,0]
	v_pk_fma_f32 v[110:111], v[128:129], v[4:5], 0 op_sel:[0,1,0] op_sel_hi:[1,1,0]
	v_pk_fma_f32 v[62:63], v[130:131], v[8:9], v[62:63] op_sel_hi:[1,0,1]
	v_pk_fma_f32 v[66:67], v[132:133], v[8:9], v[66:67] op_sel:[0,1,0] op_sel_hi:[1,1,1]
	v_pk_fma_f32 v[106:107], v[38:39], v[10:11], v[106:107] op_sel_hi:[1,0,1]
	v_pk_fma_f32 v[110:111], v[40:41], v[10:11], v[110:111] op_sel:[0,1,0] op_sel_hi:[1,1,1]
	v_pk_add_f32 v[62:63], v[62:63], v[106:107]
	v_pk_add_f32 v[66:67], v[66:67], v[110:111]
	v_pk_add_f32 v[62:63], v[62:63], v[66:67]
	s_nop 1
	v_add_f32_dpp v62, v62, v62 quad_perm:[1,0,3,2] row_mask:0xf bank_mask:0xf bound_ctrl:1
	v_add_f32_dpp v63, v63, v63 quad_perm:[1,0,3,2] row_mask:0xf bank_mask:0xf bound_ctrl:1
	s_nop 0
	v_add_f32_dpp v62, v62, v62 quad_perm:[2,3,0,1] row_mask:0xf bank_mask:0xf bound_ctrl:1
	v_add_f32_dpp v63, v63, v63 quad_perm:[2,3,0,1] row_mask:0xf bank_mask:0xf bound_ctrl:1
	v_sub_f32_e32 v116, v68, v62
	v_sub_f32_e32 v223, v112, v63
	v_fma_f32 v120, -v39, v116, v223
	v_cndmask_b32_e64 v10, v10, v116, s[10:11]
	v_cndmask_b32_e64 v11, v11, v120, s[10:11]
; #define LAS __attribute__((address_space(3)))
;     ...
; #pragma unroll
;         for (int ip = 0; ip < 32; ++ip) {
;             const int i0 = 2 * ip;
;             f32x4 rv[32];
; #pragma unroll
;             for (int jp = 0; jp <= ip; ++jp) rv[jp] = *(const LAS f32x4*)(Ad + ip * 136 + 4 * jp);
;             asm volatile("" : "+v"(lane_o) :: "memory");
;             f32x2_ a0 = {0.f, 0.f}, a1 = {0.f, 0.f}, a2 = {0.f, 0.f}, a3 = {0.f, 0.f};
; #pragma unroll
;             for (int jp = 0; jp < ip; ++jp) {
;                 const f32x2_ ta = {tr[2 * jp], tr[2 * jp]}, tb = {tr[2 * jp + 1], tr[2 * jp + 1]};
;                 const f32x2_ va = {rv[jp][0], rv[jp][1]}, vb = {rv[jp][2], rv[jp][3]};
;                 if (jp & 1) { a2 += va * ta; a3 += vb * tb; } else { a0 += va * ta; a1 += vb * tb; }
;             }
;             const f32x2_ sum = (a0 + a1) + (a2 + a3);
;             const float t0 = (lane_o == i0 ? 1.f : 0.f) - sum[0];
;             tr[i0] = t0;
;             tr[i0 + 1] = (lane_o == i0 + 1 ? 1.f : 0.f) - sum[1] - rv[ip][1] * t0;
;         }
.Lfs_row16:
	ds_read_b128 v[122:125], v14 offset:9248
	ds_read_b128 v[126:129], v14 offset:9312
	ds_read_b128 v[130:133], v14 offset:9376
	ds_read_b128 v[38:41], v14 offset:9440
	ds_read_b128 v[42:45], v14 offset:9504
	v_cmp_eq_u32_e64 s[12:13], 32, v12
	v_cmp_eq_u32_e64 s[14:15], 33, v12
	s_waitcnt lgkmcnt(5)
	v_pk_fma_f32 v[62:63], v[70:71], v[2:3], 0 op_sel_hi:[1,0,0]
	v_pk_fma_f32 v[66:67], v[72:73], v[2:3], 0 op_sel:[0,1,0] op_sel_hi:[1,1,0]
	v_cndmask_b32_e64 v68, 0, 1.0, s[12:13]
	v_cndmask_b32_e64 v112, 0, 1.0, s[14:15]
	v_pk_fma_f32 v[106:107], v[74:75], v[4:5], 0 op_sel_hi:[1,0,0]
	v_pk_fma_f32 v[110:111], v[76:77], v[4:5], 0 op_sel:[0,1,0] op_sel_hi:[1,1,0]
	v_pk_fma_f32 v[62:63], v[78:79], v[8:9], v[62:63] op_sel_hi:[1,0,1]
	v_pk_fma_f32 v[66:67], v[80:81], v[8:9], v[66:67] op_sel:[0,1,0] op_sel_hi:[1,1,1]
	v_pk_fma_f32 v[106:107], v[86:87], v[18:19], v[106:107] op_sel_hi:[1,0,1]
	v_pk_fma_f32 v[110:111], v[88:89], v[18:19], v[110:111] op_sel:[0,1,0] op_sel_hi:[1,1,1]
	v_pk_fma_f32 v[62:63], v[82:83], v[10:11], v[62:63] op_sel_hi:[1,0,1]
	v_pk_fma_f32 v[66:67], v[84:85], v[10:11], v[66:67] op_sel:[0,1,0] op_sel_hi:[1,1,1]
	v_pk_add_f32 v[62:63], v[62:63], v[106:107]
	v_pk_add_f32 v[66:67], v[66:67], v[110:111]
	v_pk_add_f32 v[62:63], v[62:63], v[66:67]
	s_nop 1
	v_add_f32_dpp v62, v62, v62 quad_perm:[1,0,3,2] row_mask:0xf bank_mask:0xf bound_ctrl:1
	v_add_f32_dpp v63, v63, v63 quad_perm:[1,0,3,2] row_mask:0xf bank_mask:0xf bound_ctrl:1
	s_nop 0
	v_add_f32_dpp v62, v62, v62 quad_perm:[2,3,0,1] row_mask:0xf bank_mask:0xf bound_ctrl:1
	v_add_f32_dpp v63, v63, v63 quad_perm:[2,3,0,1] row_mask:0xf bank_mask:0xf bound_ctrl:1
	v_sub_f32_e32 v116, v68, v62
	v_sub_f32_e32 v223, v112, v63
	v_fma_f32 v120, -v87, v116, v223
	v_cndmask_b32_e64 v18, v18, v116, s[4:5]
	v_cndmask_b32_e64 v19, v19, v120, s[4:5]
.Lfs_row17:
	ds_read_b128 v[70:73], v14 offset:9792
	ds_read_b128 v[74:77], v14 offset:9856
	ds_read_b128 v[78:81], v14 offset:9920
	ds_read_b128 v[82:85], v14 offset:9984
	ds_read_b128 v[86:89], v14 offset:10048
	v_cmp_eq_u32_e64 s[12:13], 34, v12
	v_cmp_eq_u32_e64 s[14:15], 35, v12
	s_waitcnt lgkmcnt(5)
	v_pk_fma_f32 v[62:63], v[122:123], v[2:3], 0 op_sel_hi:[1,0,0]
	v_pk_fma_f32 v[66:67], v[124:125], v[2:3], 0 op_sel:[0,1,0] op_sel_hi:[1,1,0]
	v_cndmask_b32_e64 v68, 0, 1.0, s[12:13]
	v_cndmask_b32_e64 v112, 0, 1.0, s[14:15]
	v_pk_fma_f32 v[106:107], v[126:127], v[4:5], 0 op_sel_hi:[1,0,0]
	v_pk_fma_f32 v[110:111], v[128:129], v[4:5], 0 op_sel:[0,1,0] op_sel_hi:[1,1,0]
	v_pk_fma_f32 v[62:63], v[130:131], v[8:9], v[62:63] op_sel_hi:[1,0,1]
	v_pk_fma_f32 v[66:67], v[132:133], v[8:9], v[66:67] op_sel:[0,1,0] op_sel_hi:[1,1,1]
	v_pk_fma_f32 v[106:107], v[38:39], v[10:11], v[106:107] op_sel_hi:[1,0,1]
	v_pk_fma_f32 v[110:111], v[40:41], v[10:11], v[110:111] op_sel:[0,1,0] op_sel_hi:[1,1,1]
	v_pk_fma_f32 v[62:63], v[42:43], v[18:19], v[62:63] op_sel_hi:[1,0,1]
	v_pk_fma_f32 v[66:67], v[44:45], v[18:19], v[66:67] op_sel:[0,1,0] op_sel_hi:[1,1,1]
	v_pk_add_f32 v[62:63], v[62:63], v[106:107]
	v_pk_add_f32 v[66:67], v[66:67], v[110:111]
	v_pk_add_f32 v[62:63], v[62:63], v[66:67]
	s_nop 1
	v_add_f32_dpp v62, v62, v62 quad_perm:[1,0,3,2] row_mask:0xf bank_mask:0xf bound_ctrl:1
	v_add_f32_dpp v63, v63, v63 quad_perm:[1,0,3,2] row_mask:0xf bank_mask:0xf bound_ctrl:1
	s_nop 0
	v_add_f32_dpp v62, v62, v62 quad_perm:[2,3,0,1] row_mask:0xf bank_mask:0xf bound_ctrl:1
	v_add_f32_dpp v63, v63, v63 quad_perm:[2,3,0,1] row_mask:0xf bank_mask:0xf bound_ctrl:1
	v_sub_f32_e32 v116, v68, v62
	v_sub_f32_e32 v223, v112, v63
	v_fma_f32 v120, -v43, v116, v223
	v_cndmask_b32_e64 v18, v18, v116, s[6:7]
	v_cndmask_b32_e64 v19, v19, v120, s[6:7]
.Lfs_row18:
	ds_read_b128 v[122:125], v14 offset:10336
	ds_read_b128 v[126:129], v14 offset:10400
	ds_read_b128 v[130:133], v14 offset:10464
	ds_read_b128 v[38:41], v14 offset:10528
	ds_read_b128 v[42:45], v14 offset:10592
	v_cmp_eq_u32_e64 s[12:13], 36, v12
	v_cmp_eq_u32_e64 s[14:15], 37, v12
	s_waitcnt lgkmcnt(5)
	v_pk_fma_f32 v[62:63], v[70:71], v[2:3], 0 op_sel_hi:[1,0,0]
	v_pk_fma_f32 v[66:67], v[72:73], v[2:3], 0 op_sel:[0,1,0] op_sel_hi:[1,1,0]
	v_cndmask_b32_e64 v68, 0, 1.0, s[12:13]
	v_cndmask_b32_e64 v112, 0, 1.0, s[14:15]
	v_pk_fma_f32 v[106:107], v[74:75], v[4:5], 0 op_sel_hi:[1,0,0]
	v_pk_fma_f32 v[110:111], v[76:77], v[4:5], 0 op_sel:[0,1,0] op_sel_hi:[1,1,0]
	v_pk_fma_f32 v[62:63], v[78:79], v[8:9], v[62:63] op_sel_hi:[1,0,1]
	v_pk_fma_f32 v[66:67], v[80:81], v[8:9], v[66:67] op_sel:[0,1,0] op_sel_hi:[1,1,1]
	v_pk_fma_f32 v[106:107], v[82:83], v[10:11], v[106:107] op_sel_hi:[1,0,1]
	v_pk_fma_f32 v[110:111], v[84:85], v[10:11], v[110:111] op_sel:[0,1,0] op_sel_hi:[1,1,1]
	v_pk_fma_f32 v[62:63], v[86:87], v[18:19], v[62:63] op_sel_hi:[1,0,1]
	v_pk_fma_f32 v[66:67], v[88:89], v[18:19], v[66:67] op_sel:[0,1,0] op_sel_hi:[1,1,1]
	v_pk_add_f32 v[62:63], v[62:63], v[106:107]
	v_pk_add_f32 v[66:67], v[66:67], v[110:111]
	v_pk_add_f32 v[62:63], v[62:63], v[66:67]
	s_nop 1
	v_add_f32_dpp v62, v62, v62 quad_perm:[1,0,3,2] row_mask:0xf bank_mask:0xf bound_ctrl:1
	v_add_f32_dpp v63, v63, v63 quad_perm:[1,0,3,2] row_mask:0xf bank_mask:0xf bound_ctrl:1
	s_nop 0
	v_add_f32_dpp v62, v62, v62 quad_perm:[2,3,0,1] row_mask:0xf bank_mask:0xf bound_ctrl:1
	v_add_f32_dpp v63, v63, v63 quad_perm:[2,3,0,1] row_mask:0xf bank_mask:0xf bound_ctrl:1
	v_sub_f32_e32 v116, v68, v62
	v_sub_f32_e32 v223, v112, v63
	v_fma_f32 v120, -v87, v116, v223
	v_cndmask_b32_e64 v18, v18, v116, s[8:9]
	v_cndmask_b32_e64 v19, v19, v120, s[8:9]
; #define LAS __attribute__((address_space(3)))
;     ...
; #pragma unroll
;         for (int ip = 0; ip < 32; ++ip) {
;             const int i0 = 2 * ip;
;             f32x4 rv[32];
; #pragma unroll
;             for (int jp = 0; jp <= ip; ++jp) rv[jp] = *(const LAS f32x4*)(Ad + ip * 136 + 4 * jp);
;             asm volatile("" : "+v"(lane_o) :: "memory");
;             f32x2_ a0 = {0.f, 0.f}, a1 = {0.f, 0.f}, a2 = {0.f, 0.f}, a3 = {0.f, 0.f};
; #pragma unroll
;             for (int jp = 0; jp < ip; ++jp) {
;                 const f32x2_ ta = {tr[2 * jp], tr[2 * jp]}, tb = {tr[2 * jp + 1], tr[2 * jp + 1]};
;                 const f32x2_ va = {rv[jp][0], rv[jp][1]}, vb = {rv[jp][2], rv[jp][3]};
;                 if (jp & 1) { a2 += va * ta; a3 += vb * tb; } else { a0 += va * ta; a1 += vb * tb; }
;             }
;             const f32x2_ sum = (a0 + a1) + (a2 + a3);
;             const float t0 = (lane_o == i0 ? 1.f : 0.f) - sum[0];
;             tr[i0] = t0;
;             tr[i0 + 1] = (lane_o == i0 + 1 ? 1.f : 0.f) - sum[1] - rv[ip][1] * t0;
;         }
.Lfs_row19:
	ds_read_b128 v[70:73], v14 offset:10880
	ds_read_b128 v[74:77], v14 offset:10944
	ds_read_b128 v[78:81], v14 offset:11008
	ds_read_b128 v[82:85], v14 offset:11072
	ds_read_b128 v[86:89], v14 offset:11136
	ds_read_b128 v[90:93], v14 offset:11200
	v_cmp_eq_u32_e64 s[12:13], 38, v12
	v_cmp_eq_u32_e64 s[14:15], 39, v12
	s_waitcnt lgkmcnt(6)
	v_pk_fma_f32 v[62:63], v[122:123], v[2:3], 0 op_sel_hi:[1,0,0]
	v_pk_fma_f32 v[66:67], v[124:125], v[2:3], 0 op_sel:[0,1,0] op_sel_hi:[1,1,0]
	v_cndmask_b32_e64 v68, 0, 1.0, s[12:13]
	v_cndmask_b32_e64 v112, 0, 1.0, s[14:15]
	v_pk_fma_f32 v[106:107], v[126:127], v[4:5], 0 op_sel_hi:[1,0,0]
	v_pk_fma_f32 v[110:111], v[128:129], v[4:5], 0 op_sel:[0,1,0] op_sel_hi:[1,1,0]
	v_pk_fma_f32 v[62:63], v[130:131], v[8:9], v[62:63] op_sel_hi:[1,0,1]
	v_pk_fma_f32 v[66:67], v[132:133], v[8:9], v[66:67] op_sel:[0,1,0] op_sel_hi:[1,1,1]
	v_pk_fma_f32 v[106:107], v[38:39], v[10:11], v[106:107] op_sel_hi:[1,0,1]
	v_pk_fma_f32 v[110:111], v[40:41], v[10:11], v[110:111] op_sel:[0,1,0] op_sel_hi:[1,1,1]
	v_pk_fma_f32 v[62:63], v[42:43], v[18:19], v[62:63] op_sel_hi:[1,0,1]
	v_pk_fma_f32 v[66:67], v[44:45], v[18:19], v[66:67] op_sel:[0,1,0] op_sel_hi:[1,1,1]
	v_pk_add_f32 v[62:63], v[62:63], v[106:107]
	v_pk_add_f32 v[66:67], v[66:67], v[110:111]
	v_pk_add_f32 v[62:63], v[62:63], v[66:67]
	s_nop 1
	v_add_f32_dpp v62, v62, v62 quad_perm:[1,0,3,2] row_mask:0xf bank_mask:0xf bound_ctrl:1
	v_add_f32_dpp v63, v63, v63 quad_perm:[1,0,3,2] row_mask:0xf bank_mask:0xf bound_ctrl:1
	s_nop 0
	v_add_f32_dpp v62, v62, v62 quad_perm:[2,3,0,1] row_mask:0xf bank_mask:0xf bound_ctrl:1
	v_add_f32_dpp v63, v63, v63 quad_perm:[2,3,0,1] row_mask:0xf bank_mask:0xf bound_ctrl:1
	v_sub_f32_e32 v116, v68, v62
	v_sub_f32_e32 v223, v112, v63
	v_fma_f32 v120, -v43, v116, v223
	v_cndmask_b32_e64 v18, v18, v116, s[10:11]
	v_cndmask_b32_e64 v19, v19, v120, s[10:11]
.Lfs_row20:
	ds_read_b128 v[122:125], v14 offset:11424
	ds_read_b128 v[126:129], v14 offset:11488
	ds_read_b128 v[130:133], v14 offset:11552
	ds_read_b128 v[38:41], v14 offset:11616
	ds_read_b128 v[42:45], v14 offset:11680
	ds_read_b128 v[46:49], v14 offset:11744
	v_cmp_eq_u32_e64 s[12:13], 40, v12
	v_cmp_eq_u32_e64 s[14:15], 41, v12
	s_waitcnt lgkmcnt(6)
	v_pk_fma_f32 v[62:63], v[70:71], v[2:3], 0 op_sel_hi:[1,0,0]
	v_pk_fma_f32 v[66:67], v[72:73], v[2:3], 0 op_sel:[0,1,0] op_sel_hi:[1,1,0]
	v_cndmask_b32_e64 v68, 0, 1.0, s[12:13]
	v_cndmask_b32_e64 v112, 0, 1.0, s[14:15]
	v_pk_fma_f32 v[106:107], v[74:75], v[4:5], 0 op_sel_hi:[1,0,0]
	v_pk_fma_f32 v[110:111], v[76:77], v[4:5], 0 op_sel:[0,1,0] op_sel_hi:[1,1,0]
	v_pk_fma_f32 v[62:63], v[78:79], v[8:9], v[62:63] op_sel_hi:[1,0,1]
	v_pk_fma_f32 v[66:67], v[80:81], v[8:9], v[66:67] op_sel:[0,1,0] op_sel_hi:[1,1,1]
	v_pk_fma_f32 v[106:107], v[82:83], v[10:11], v[106:107] op_sel_hi:[1,0,1]
	v_pk_fma_f32 v[110:111], v[84:85], v[10:11], v[110:111] op_sel:[0,1,0] op_sel_hi:[1,1,1]
	v_pk_fma_f32 v[62:63], v[90:91], v[50:51], v[62:63] op_sel_hi:[1,0,1]
	v_pk_fma_f32 v[66:67], v[92:93], v[50:51], v[66:67] op_sel:[0,1,0] op_sel_hi:[1,1,1]
	v_pk_fma_f32 v[106:107], v[86:87], v[18:19], v[106:107] op_sel_hi:[1,0,1]
	v_pk_fma_f32 v[110:111], v[88:89], v[18:19], v[110:111] op_sel:[0,1,0] op_sel_hi:[1,1,1]
	v_pk_add_f32 v[62:63], v[62:63], v[106:107]
	v_pk_add_f32 v[66:67], v[66:67], v[110:111]
	v_pk_add_f32 v[62:63], v[62:63], v[66:67]
	s_nop 1
	v_add_f32_dpp v62, v62, v62 quad_perm:[1,0,3,2] row_mask:0xf bank_mask:0xf bound_ctrl:1
	v_add_f32_dpp v63, v63, v63 quad_perm:[1,0,3,2] row_mask:0xf bank_mask:0xf bound_ctrl:1
	s_nop 0
	v_add_f32_dpp v62, v62, v62 quad_perm:[2,3,0,1] row_mask:0xf bank_mask:0xf bound_ctrl:1
	v_add_f32_dpp v63, v63, v63 quad_perm:[2,3,0,1] row_mask:0xf bank_mask:0xf bound_ctrl:1
	v_sub_f32_e32 v116, v68, v62
	v_sub_f32_e32 v223, v112, v63
	v_fma_f32 v120, -v91, v116, v223
	v_cndmask_b32_e64 v50, v50, v116, s[4:5]
	v_cndmask_b32_e64 v51, v51, v120, s[4:5]
.Lfs_row21:
	ds_read_b128 v[70:73], v14 offset:11968
	ds_read_b128 v[74:77], v14 offset:12032
	ds_read_b128 v[78:81], v14 offset:12096
	ds_read_b128 v[82:85], v14 offset:12160
	ds_read_b128 v[86:89], v14 offset:12224
	ds_read_b128 v[90:93], v14 offset:12288
	v_cmp_eq_u32_e64 s[12:13], 42, v12
	v_cmp_eq_u32_e64 s[14:15], 43, v12
	s_waitcnt lgkmcnt(6)
	v_pk_fma_f32 v[62:63], v[122:123], v[2:3], 0 op_sel_hi:[1,0,0]
	v_pk_fma_f32 v[66:67], v[124:125], v[2:3], 0 op_sel:[0,1,0] op_sel_hi:[1,1,0]
	v_cndmask_b32_e64 v68, 0, 1.0, s[12:13]
	v_cndmask_b32_e64 v112, 0, 1.0, s[14:15]
	v_pk_fma_f32 v[106:107], v[126:127], v[4:5], 0 op_sel_hi:[1,0,0]
	v_pk_fma_f32 v[110:111], v[128:129], v[4:5], 0 op_sel:[0,1,0] op_sel_hi:[1,1,0]
	v_pk_fma_f32 v[62:63], v[130:131], v[8:9], v[62:63] op_sel_hi:[1,0,1]
	v_pk_fma_f32 v[66:67], v[132:133], v[8:9], v[66:67] op_sel:[0,1,0] op_sel_hi:[1,1,1]
	v_pk_fma_f32 v[106:107], v[38:39], v[10:11], v[106:107] op_sel_hi:[1,0,1]
	v_pk_fma_f32 v[110:111], v[40:41], v[10:11], v[110:111] op_sel:[0,1,0] op_sel_hi:[1,1,1]
	v_pk_fma_f32 v[62:63], v[42:43], v[18:19], v[62:63] op_sel_hi:[1,0,1]
	v_pk_fma_f32 v[66:67], v[44:45], v[18:19], v[66:67] op_sel:[0,1,0] op_sel_hi:[1,1,1]
	v_pk_fma_f32 v[106:107], v[46:47], v[50:51], v[106:107] op_sel_hi:[1,0,1]
	v_pk_fma_f32 v[110:111], v[48:49], v[50:51], v[110:111] op_sel:[0,1,0] op_sel_hi:[1,1,1]
	v_pk_add_f32 v[62:63], v[62:63], v[106:107]
	v_pk_add_f32 v[66:67], v[66:67], v[110:111]
	v_pk_add_f32 v[62:63], v[62:63], v[66:67]
	s_nop 1
	v_add_f32_dpp v62, v62, v62 quad_perm:[1,0,3,2] row_mask:0xf bank_mask:0xf bound_ctrl:1
	v_add_f32_dpp v63, v63, v63 quad_perm:[1,0,3,2] row_mask:0xf bank_mask:0xf bound_ctrl:1
	s_nop 0
	v_add_f32_dpp v62, v62, v62 quad_perm:[2,3,0,1] row_mask:0xf bank_mask:0xf bound_ctrl:1
	v_add_f32_dpp v63, v63, v63 quad_perm:[2,3,0,1] row_mask:0xf bank_mask:0xf bound_ctrl:1
	v_sub_f32_e32 v116, v68, v62
	v_sub_f32_e32 v223, v112, v63
	v_fma_f32 v120, -v47, v116, v223
	v_cndmask_b32_e64 v50, v50, v116, s[6:7]
	v_cndmask_b32_e64 v51, v51, v120, s[6:7]
; #define LAS __attribute__((address_space(3)))
;     ...
; #pragma unroll
;         for (int ip = 0; ip < 32; ++ip) {
;             const int i0 = 2 * ip;
;             f32x4 rv[32];
; #pragma unroll
;             for (int jp = 0; jp <= ip; ++jp) rv[jp] = *(const LAS f32x4*)(Ad + ip * 136 + 4 * jp);
;             asm volatile("" : "+v"(lane_o) :: "memory");
;             f32x2_ a0 = {0.f, 0.f}, a1 = {0.f, 0.f}, a2 = {0.f, 0.f}, a3 = {0.f, 0.f};
; #pragma unroll
;             for (int jp = 0; jp < ip; ++jp) {
;                 const f32x2_ ta = {tr[2 * jp], tr[2 * jp]}, tb = {tr[2 * jp + 1], tr[2 * jp + 1]};
;                 const f32x2_ va = {rv[jp][0], rv[jp][1]}, vb = {rv[jp][2], rv[jp][3]};
;                 if (jp & 1) { a2 += va * ta; a3 += vb * tb; } else { a0 += va * ta; a1 += vb * tb; }
;             }
;             const f32x2_ sum = (a0 + a1) + (a2 + a3);
;             const float t0 = (lane_o == i0 ? 1.f : 0.f) - sum[0];
;             tr[i0] = t0;
;             tr[i0 + 1] = (lane_o == i0 + 1 ? 1.f : 0.f) - sum[1] - rv[ip][1] * t0;
;         }
.Lfs_row22:
	ds_read_b128 v[122:125], v14 offset:12512
	ds_read_b128 v[126:129], v14 offset:12576
	ds_read_b128 v[130:133], v14 offset:12640
	ds_read_b128 v[38:41], v14 offset:12704
	ds_read_b128 v[42:45], v14 offset:12768
	ds_read_b128 v[46:49], v14 offset:12832
	v_cmp_eq_u32_e64 s[12:13], 44, v12
	v_cmp_eq_u32_e64 s[14:15], 45, v12
	s_waitcnt lgkmcnt(6)
	v_pk_fma_f32 v[62:63], v[70:71], v[2:3], 0 op_sel_hi:[1,0,0]
	v_pk_fma_f32 v[66:67], v[72:73], v[2:3], 0 op_sel:[0,1,0] op_sel_hi:[1,1,0]
	v_cndmask_b32_e64 v68, 0, 1.0, s[12:13]
	v_cndmask_b32_e64 v112, 0, 1.0, s[14:15]
	v_pk_fma_f32 v[106:107], v[74:75], v[4:5], 0 op_sel_hi:[1,0,0]
	v_pk_fma_f32 v[110:111], v[76:77], v[4:5], 0 op_sel:[0,1,0] op_sel_hi:[1,1,0]
	v_pk_fma_f32 v[62:63], v[78:79], v[8:9], v[62:63] op_sel_hi:[1,0,1]
	v_pk_fma_f32 v[66:67], v[80:81], v[8:9], v[66:67] op_sel:[0,1,0] op_sel_hi:[1,1,1]
	v_pk_fma_f32 v[106:107], v[82:83], v[10:11], v[106:107] op_sel_hi:[1,0,1]
	v_pk_fma_f32 v[110:111], v[84:85], v[10:11], v[110:111] op_sel:[0,1,0] op_sel_hi:[1,1,1]
	v_pk_fma_f32 v[62:63], v[86:87], v[18:19], v[62:63] op_sel_hi:[1,0,1]
	v_pk_fma_f32 v[66:67], v[88:89], v[18:19], v[66:67] op_sel:[0,1,0] op_sel_hi:[1,1,1]
	v_pk_fma_f32 v[106:107], v[90:91], v[50:51], v[106:107] op_sel_hi:[1,0,1]
	v_pk_fma_f32 v[110:111], v[92:93], v[50:51], v[110:111] op_sel:[0,1,0] op_sel_hi:[1,1,1]
	v_pk_add_f32 v[62:63], v[62:63], v[106:107]
	v_pk_add_f32 v[66:67], v[66:67], v[110:111]
	v_pk_add_f32 v[62:63], v[62:63], v[66:67]
	s_nop 1
	v_add_f32_dpp v62, v62, v62 quad_perm:[1,0,3,2] row_mask:0xf bank_mask:0xf bound_ctrl:1
	v_add_f32_dpp v63, v63, v63 quad_perm:[1,0,3,2] row_mask:0xf bank_mask:0xf bound_ctrl:1
	s_nop 0
	v_add_f32_dpp v62, v62, v62 quad_perm:[2,3,0,1] row_mask:0xf bank_mask:0xf bound_ctrl:1
	v_add_f32_dpp v63, v63, v63 quad_perm:[2,3,0,1] row_mask:0xf bank_mask:0xf bound_ctrl:1
	v_sub_f32_e32 v116, v68, v62
	v_sub_f32_e32 v223, v112, v63
	v_fma_f32 v120, -v91, v116, v223
	v_cndmask_b32_e64 v50, v50, v116, s[8:9]
	v_cndmask_b32_e64 v51, v51, v120, s[8:9]
.Lfs_row23:
	ds_read_b128 v[70:73], v14 offset:13056
	ds_read_b128 v[74:77], v14 offset:13120
	ds_read_b128 v[78:81], v14 offset:13184
	ds_read_b128 v[82:85], v14 offset:13248
	ds_read_b128 v[86:89], v14 offset:13312
	ds_read_b128 v[90:93], v14 offset:13376
	ds_read_b128 v[94:97], v14 offset:13440
	v_cmp_eq_u32_e64 s[12:13], 46, v12
	v_cmp_eq_u32_e64 s[14:15], 47, v12
	s_waitcnt lgkmcnt(7)
	v_pk_fma_f32 v[62:63], v[122:123], v[2:3], 0 op_sel_hi:[1,0,0]
	v_pk_fma_f32 v[66:67], v[124:125], v[2:3], 0 op_sel:[0,1,0] op_sel_hi:[1,1,0]
	v_cndmask_b32_e64 v68, 0, 1.0, s[12:13]
	v_cndmask_b32_e64 v112, 0, 1.0, s[14:15]
	v_pk_fma_f32 v[106:107], v[126:127], v[4:5], 0 op_sel_hi:[1,0,0]
	v_pk_fma_f32 v[110:111], v[128:129], v[4:5], 0 op_sel:[0,1,0] op_sel_hi:[1,1,0]
	v_pk_fma_f32 v[62:63], v[130:131], v[8:9], v[62:63] op_sel_hi:[1,0,1]
	v_pk_fma_f32 v[66:67], v[132:133], v[8:9], v[66:67] op_sel:[0,1,0] op_sel_hi:[1,1,1]
	v_pk_fma_f32 v[106:107], v[38:39], v[10:11], v[106:107] op_sel_hi:[1,0,1]
	v_pk_fma_f32 v[110:111], v[40:41], v[10:11], v[110:111] op_sel:[0,1,0] op_sel_hi:[1,1,1]
	v_pk_fma_f32 v[62:63], v[42:43], v[18:19], v[62:63] op_sel_hi:[1,0,1]
	v_pk_fma_f32 v[66:67], v[44:45], v[18:19], v[66:67] op_sel:[0,1,0] op_sel_hi:[1,1,1]
	v_pk_fma_f32 v[106:107], v[46:47], v[50:51], v[106:107] op_sel_hi:[1,0,1]
	v_pk_fma_f32 v[110:111], v[48:49], v[50:51], v[110:111] op_sel:[0,1,0] op_sel_hi:[1,1,1]
	v_pk_add_f32 v[62:63], v[62:63], v[106:107]
	v_pk_add_f32 v[66:67], v[66:67], v[110:111]
	v_pk_add_f32 v[62:63], v[62:63], v[66:67]
	s_nop 1
	v_add_f32_dpp v62, v62, v62 quad_perm:[1,0,3,2] row_mask:0xf bank_mask:0xf bound_ctrl:1
	v_add_f32_dpp v63, v63, v63 quad_perm:[1,0,3,2] row_mask:0xf bank_mask:0xf bound_ctrl:1
	s_nop 0
	v_add_f32_dpp v62, v62, v62 quad_perm:[2,3,0,1] row_mask:0xf bank_mask:0xf bound_ctrl:1
	v_add_f32_dpp v63, v63, v63 quad_perm:[2,3,0,1] row_mask:0xf bank_mask:0xf bound_ctrl:1
	v_sub_f32_e32 v116, v68, v62
	v_sub_f32_e32 v223, v112, v63
	v_fma_f32 v120, -v47, v116, v223
	v_cndmask_b32_e64 v50, v50, v116, s[10:11]
	v_cndmask_b32_e64 v51, v51, v120, s[10:11]
.Lfs_row24:
	ds_read_b128 v[122:125], v14 offset:13600
	ds_read_b128 v[126:129], v14 offset:13664
	ds_read_b128 v[130:133], v14 offset:13728
	ds_read_b128 v[38:41], v14 offset:13792
	ds_read_b128 v[42:45], v14 offset:13856
	ds_read_b128 v[46:49], v14 offset:13920
	ds_read_b128 v[102:105], v14 offset:13984
	v_cmp_eq_u32_e64 s[12:13], 48, v12
	v_cmp_eq_u32_e64 s[14:15], 49, v12
	s_waitcnt lgkmcnt(7)
	v_pk_fma_f32 v[62:63], v[70:71], v[2:3], 0 op_sel_hi:[1,0,0]
	v_pk_fma_f32 v[66:67], v[72:73], v[2:3], 0 op_sel:[0,1,0] op_sel_hi:[1,1,0]
	v_cndmask_b32_e64 v68, 0, 1.0, s[12:13]
	v_cndmask_b32_e64 v112, 0, 1.0, s[14:15]
	v_pk_fma_f32 v[106:107], v[74:75], v[4:5], 0 op_sel_hi:[1,0,0]
	v_pk_fma_f32 v[110:111], v[76:77], v[4:5], 0 op_sel:[0,1,0] op_sel_hi:[1,1,0]
	v_pk_fma_f32 v[62:63], v[78:79], v[8:9], v[62:63] op_sel_hi:[1,0,1]
	v_pk_fma_f32 v[66:67], v[80:81], v[8:9], v[66:67] op_sel:[0,1,0] op_sel_hi:[1,1,1]
	v_pk_fma_f32 v[106:107], v[82:83], v[10:11], v[106:107] op_sel_hi:[1,0,1]
	v_pk_fma_f32 v[110:111], v[84:85], v[10:11], v[110:111] op_sel:[0,1,0] op_sel_hi:[1,1,1]
	v_pk_fma_f32 v[62:63], v[86:87], v[18:19], v[62:63] op_sel_hi:[1,0,1]
	v_pk_fma_f32 v[66:67], v[88:89], v[18:19], v[66:67] op_sel:[0,1,0] op_sel_hi:[1,1,1]
	v_pk_fma_f32 v[106:107], v[94:95], v[54:55], v[106:107] op_sel_hi:[1,0,1]
	v_pk_fma_f32 v[110:111], v[96:97], v[54:55], v[110:111] op_sel:[0,1,0] op_sel_hi:[1,1,1]
	v_pk_fma_f32 v[62:63], v[90:91], v[50:51], v[62:63] op_sel_hi:[1,0,1]
	v_pk_fma_f32 v[66:67], v[92:93], v[50:51], v[66:67] op_sel:[0,1,0] op_sel_hi:[1,1,1]
	v_pk_add_f32 v[62:63], v[62:63], v[106:107]
	v_pk_add_f32 v[66:67], v[66:67], v[110:111]
	v_pk_add_f32 v[62:63], v[62:63], v[66:67]
	s_nop 1
	v_add_f32_dpp v62, v62, v62 quad_perm:[1,0,3,2] row_mask:0xf bank_mask:0xf bound_ctrl:1
	v_add_f32_dpp v63, v63, v63 quad_perm:[1,0,3,2] row_mask:0xf bank_mask:0xf bound_ctrl:1
	s_nop 0
	v_add_f32_dpp v62, v62, v62 quad_perm:[2,3,0,1] row_mask:0xf bank_mask:0xf bound_ctrl:1
	v_add_f32_dpp v63, v63, v63 quad_perm:[2,3,0,1] row_mask:0xf bank_mask:0xf bound_ctrl:1
	v_sub_f32_e32 v116, v68, v62
	v_sub_f32_e32 v223, v112, v63
	v_fma_f32 v120, -v95, v116, v223
	v_cndmask_b32_e64 v54, v54, v116, s[4:5]
	v_cndmask_b32_e64 v55, v55, v120, s[4:5]
; #define LAS __attribute__((address_space(3)))
;     ...
; #pragma unroll
;         for (int ip = 0; ip < 32; ++ip) {
;             const int i0 = 2 * ip;
;             f32x4 rv[32];
; #pragma unroll
;             for (int jp = 0; jp <= ip; ++jp) rv[jp] = *(const LAS f32x4*)(Ad + ip * 136 + 4 * jp);
;             asm volatile("" : "+v"(lane_o) :: "memory");
;             f32x2_ a0 = {0.f, 0.f}, a1 = {0.f, 0.f}, a2 = {0.f, 0.f}, a3 = {0.f, 0.f};
; #pragma unroll
;             for (int jp = 0; jp < ip; ++jp) {
;                 const f32x2_ ta = {tr[2 * jp], tr[2 * jp]}, tb = {tr[2 * jp + 1], tr[2 * jp + 1]};
;                 const f32x2_ va = {rv[jp][0], rv[jp][1]}, vb = {rv[jp][2], rv[jp][3]};
;                 if (jp & 1) { a2 += va * ta; a3 += vb * tb; } else { a0 += va * ta; a1 += vb * tb; }
;             }
;             const f32x2_ sum = (a0 + a1) + (a2 + a3);
;             const float t0 = (lane_o == i0 ? 1.f : 0.f) - sum[0];
;             tr[i0] = t0;
;             tr[i0 + 1] = (lane_o == i0 + 1 ? 1.f : 0.f) - sum[1] - rv[ip][1] * t0;
;         }
.Lfs_row25:
	ds_read_b128 v[70:73], v14 offset:14144
	ds_read_b128 v[74:77], v14 offset:14208
	ds_read_b128 v[78:81], v14 offset:14272
	ds_read_b128 v[82:85], v14 offset:14336
	ds_read_b128 v[86:89], v14 offset:14400
	ds_read_b128 v[90:93], v14 offset:14464
	ds_read_b128 v[94:97], v14 offset:14528
	v_cmp_eq_u32_e64 s[12:13], 50, v12
	v_cmp_eq_u32_e64 s[14:15], 51, v12
	s_waitcnt lgkmcnt(7)
	v_pk_fma_f32 v[62:63], v[122:123], v[2:3], 0 op_sel_hi:[1,0,0]
	v_pk_fma_f32 v[66:67], v[124:125], v[2:3], 0 op_sel:[0,1,0] op_sel_hi:[1,1,0]
	v_cndmask_b32_e64 v68, 0, 1.0, s[12:13]
	v_cndmask_b32_e64 v112, 0, 1.0, s[14:15]
	v_pk_fma_f32 v[106:107], v[126:127], v[4:5], 0 op_sel_hi:[1,0,0]
	v_pk_fma_f32 v[110:111], v[128:129], v[4:5], 0 op_sel:[0,1,0] op_sel_hi:[1,1,0]
	v_pk_fma_f32 v[62:63], v[130:131], v[8:9], v[62:63] op_sel_hi:[1,0,1]
	v_pk_fma_f32 v[66:67], v[132:133], v[8:9], v[66:67] op_sel:[0,1,0] op_sel_hi:[1,1,1]
	v_pk_fma_f32 v[106:107], v[38:39], v[10:11], v[106:107] op_sel_hi:[1,0,1]
	v_pk_fma_f32 v[110:111], v[40:41], v[10:11], v[110:111] op_sel:[0,1,0] op_sel_hi:[1,1,1]
	v_pk_fma_f32 v[62:63], v[42:43], v[18:19], v[62:63] op_sel_hi:[1,0,1]
	v_pk_fma_f32 v[66:67], v[44:45], v[18:19], v[66:67] op_sel:[0,1,0] op_sel_hi:[1,1,1]
	v_pk_fma_f32 v[106:107], v[46:47], v[50:51], v[106:107] op_sel_hi:[1,0,1]
	v_pk_fma_f32 v[110:111], v[48:49], v[50:51], v[110:111] op_sel:[0,1,0] op_sel_hi:[1,1,1]
	v_pk_fma_f32 v[62:63], v[102:103], v[54:55], v[62:63] op_sel_hi:[1,0,1]
	v_pk_fma_f32 v[66:67], v[104:105], v[54:55], v[66:67] op_sel:[0,1,0] op_sel_hi:[1,1,1]
	v_pk_add_f32 v[62:63], v[62:63], v[106:107]
	v_pk_add_f32 v[66:67], v[66:67], v[110:111]
	v_pk_add_f32 v[62:63], v[62:63], v[66:67]
	s_nop 1
	v_add_f32_dpp v62, v62, v62 quad_perm:[1,0,3,2] row_mask:0xf bank_mask:0xf bound_ctrl:1
	v_add_f32_dpp v63, v63, v63 quad_perm:[1,0,3,2] row_mask:0xf bank_mask:0xf bound_ctrl:1
	s_nop 0
	v_add_f32_dpp v62, v62, v62 quad_perm:[2,3,0,1] row_mask:0xf bank_mask:0xf bound_ctrl:1
	v_add_f32_dpp v63, v63, v63 quad_perm:[2,3,0,1] row_mask:0xf bank_mask:0xf bound_ctrl:1
	v_sub_f32_e32 v116, v68, v62
	v_sub_f32_e32 v223, v112, v63
	v_fma_f32 v120, -v103, v116, v223
	v_cndmask_b32_e64 v54, v54, v116, s[6:7]
	v_cndmask_b32_e64 v55, v55, v120, s[6:7]
.Lfs_row26:
	ds_read_b128 v[122:125], v14 offset:14688
	ds_read_b128 v[126:129], v14 offset:14752
	ds_read_b128 v[130:133], v14 offset:14816
	ds_read_b128 v[38:41], v14 offset:14880
	ds_read_b128 v[42:45], v14 offset:14944
	ds_read_b128 v[46:49], v14 offset:15008
	ds_read_b128 v[102:105], v14 offset:15072
	v_cmp_eq_u32_e64 s[12:13], 52, v12
	v_cmp_eq_u32_e64 s[14:15], 53, v12
	s_waitcnt lgkmcnt(7)
	v_pk_fma_f32 v[62:63], v[70:71], v[2:3], 0 op_sel_hi:[1,0,0]
	v_pk_fma_f32 v[66:67], v[72:73], v[2:3], 0 op_sel:[0,1,0] op_sel_hi:[1,1,0]
	v_cndmask_b32_e64 v68, 0, 1.0, s[12:13]
	v_cndmask_b32_e64 v112, 0, 1.0, s[14:15]
	v_pk_fma_f32 v[106:107], v[74:75], v[4:5], 0 op_sel_hi:[1,0,0]
	v_pk_fma_f32 v[110:111], v[76:77], v[4:5], 0 op_sel:[0,1,0] op_sel_hi:[1,1,0]
	v_pk_fma_f32 v[62:63], v[78:79], v[8:9], v[62:63] op_sel_hi:[1,0,1]
	v_pk_fma_f32 v[66:67], v[80:81], v[8:9], v[66:67] op_sel:[0,1,0] op_sel_hi:[1,1,1]
	v_pk_fma_f32 v[106:107], v[82:83], v[10:11], v[106:107] op_sel_hi:[1,0,1]
	v_pk_fma_f32 v[110:111], v[84:85], v[10:11], v[110:111] op_sel:[0,1,0] op_sel_hi:[1,1,1]
	v_pk_fma_f32 v[62:63], v[86:87], v[18:19], v[62:63] op_sel_hi:[1,0,1]
	v_pk_fma_f32 v[66:67], v[88:89], v[18:19], v[66:67] op_sel:[0,1,0] op_sel_hi:[1,1,1]
	v_pk_fma_f32 v[106:107], v[90:91], v[50:51], v[106:107] op_sel_hi:[1,0,1]
	v_pk_fma_f32 v[110:111], v[92:93], v[50:51], v[110:111] op_sel:[0,1,0] op_sel_hi:[1,1,1]
	v_pk_fma_f32 v[62:63], v[94:95], v[54:55], v[62:63] op_sel_hi:[1,0,1]
	v_pk_fma_f32 v[66:67], v[96:97], v[54:55], v[66:67] op_sel:[0,1,0] op_sel_hi:[1,1,1]
	v_pk_add_f32 v[62:63], v[62:63], v[106:107]
	v_pk_add_f32 v[66:67], v[66:67], v[110:111]
	v_pk_add_f32 v[62:63], v[62:63], v[66:67]
	s_nop 1
	v_add_f32_dpp v62, v62, v62 quad_perm:[1,0,3,2] row_mask:0xf bank_mask:0xf bound_ctrl:1
	v_add_f32_dpp v63, v63, v63 quad_perm:[1,0,3,2] row_mask:0xf bank_mask:0xf bound_ctrl:1
	s_nop 0
	v_add_f32_dpp v62, v62, v62 quad_perm:[2,3,0,1] row_mask:0xf bank_mask:0xf bound_ctrl:1
	v_add_f32_dpp v63, v63, v63 quad_perm:[2,3,0,1] row_mask:0xf bank_mask:0xf bound_ctrl:1
	v_sub_f32_e32 v116, v68, v62
	v_sub_f32_e32 v223, v112, v63
	v_fma_f32 v120, -v95, v116, v223
	v_cndmask_b32_e64 v54, v54, v116, s[8:9]
	v_cndmask_b32_e64 v55, v55, v120, s[8:9]
; #define LAS __attribute__((address_space(3)))
;     ...
; #pragma unroll
;         for (int ip = 0; ip < 32; ++ip) {
;             const int i0 = 2 * ip;
;             f32x4 rv[32];
; #pragma unroll
;             for (int jp = 0; jp <= ip; ++jp) rv[jp] = *(const LAS f32x4*)(Ad + ip * 136 + 4 * jp);
;             asm volatile("" : "+v"(lane_o) :: "memory");
;             f32x2_ a0 = {0.f, 0.f}, a1 = {0.f, 0.f}, a2 = {0.f, 0.f}, a3 = {0.f, 0.f};
; #pragma unroll
;             for (int jp = 0; jp < ip; ++jp) {
;                 const f32x2_ ta = {tr[2 * jp], tr[2 * jp]}, tb = {tr[2 * jp + 1], tr[2 * jp + 1]};
;                 const f32x2_ va = {rv[jp][0], rv[jp][1]}, vb = {rv[jp][2], rv[jp][3]};
;                 if (jp & 1) { a2 += va * ta; a3 += vb * tb; } else { a0 += va * ta; a1 += vb * tb; }
;             }
;             const f32x2_ sum = (a0 + a1) + (a2 + a3);
;             const float t0 = (lane_o == i0 ? 1.f : 0.f) - sum[0];
;             tr[i0] = t0;
;             tr[i0 + 1] = (lane_o == i0 + 1 ? 1.f : 0.f) - sum[1] - rv[ip][1] * t0;
;         }
.Lfs_row27:
	ds_read_b128 v[70:73], v14 offset:15232
	ds_read_b128 v[74:77], v14 offset:15296
	ds_read_b128 v[78:81], v14 offset:15360
	ds_read_b128 v[82:85], v14 offset:15424
	ds_read_b128 v[86:89], v14 offset:15488
	ds_read_b128 v[90:93], v14 offset:15552
	ds_read_b128 v[94:97], v14 offset:15616
	ds_read_b128 v[98:101], v14 offset:15680
	v_cmp_eq_u32_e64 s[12:13], 54, v12
	v_cmp_eq_u32_e64 s[14:15], 55, v12
	s_waitcnt lgkmcnt(8)
	v_pk_fma_f32 v[62:63], v[122:123], v[2:3], 0 op_sel_hi:[1,0,0]
	v_pk_fma_f32 v[66:67], v[124:125], v[2:3], 0 op_sel:[0,1,0] op_sel_hi:[1,1,0]
	v_cndmask_b32_e64 v68, 0, 1.0, s[12:13]
	v_cndmask_b32_e64 v112, 0, 1.0, s[14:15]
	v_pk_fma_f32 v[106:107], v[126:127], v[4:5], 0 op_sel_hi:[1,0,0]
	v_pk_fma_f32 v[110:111], v[128:129], v[4:5], 0 op_sel:[0,1,0] op_sel_hi:[1,1,0]
	v_pk_fma_f32 v[62:63], v[130:131], v[8:9], v[62:63] op_sel_hi:[1,0,1]
	v_pk_fma_f32 v[66:67], v[132:133], v[8:9], v[66:67] op_sel:[0,1,0] op_sel_hi:[1,1,1]
	v_pk_fma_f32 v[106:107], v[38:39], v[10:11], v[106:107] op_sel_hi:[1,0,1]
	v_pk_fma_f32 v[110:111], v[40:41], v[10:11], v[110:111] op_sel:[0,1,0] op_sel_hi:[1,1,1]
	v_pk_fma_f32 v[62:63], v[42:43], v[18:19], v[62:63] op_sel_hi:[1,0,1]
	v_pk_fma_f32 v[66:67], v[44:45], v[18:19], v[66:67] op_sel:[0,1,0] op_sel_hi:[1,1,1]
	v_pk_fma_f32 v[106:107], v[46:47], v[50:51], v[106:107] op_sel_hi:[1,0,1]
	v_pk_fma_f32 v[110:111], v[48:49], v[50:51], v[110:111] op_sel:[0,1,0] op_sel_hi:[1,1,1]
	v_pk_fma_f32 v[62:63], v[102:103], v[54:55], v[62:63] op_sel_hi:[1,0,1]
	v_pk_fma_f32 v[66:67], v[104:105], v[54:55], v[66:67] op_sel:[0,1,0] op_sel_hi:[1,1,1]
	v_pk_add_f32 v[62:63], v[62:63], v[106:107]
	v_pk_add_f32 v[66:67], v[66:67], v[110:111]
	v_pk_add_f32 v[62:63], v[62:63], v[66:67]
	s_nop 1
	v_add_f32_dpp v62, v62, v62 quad_perm:[1,0,3,2] row_mask:0xf bank_mask:0xf bound_ctrl:1
	v_add_f32_dpp v63, v63, v63 quad_perm:[1,0,3,2] row_mask:0xf bank_mask:0xf bound_ctrl:1
	s_nop 0
	v_add_f32_dpp v62, v62, v62 quad_perm:[2,3,0,1] row_mask:0xf bank_mask:0xf bound_ctrl:1
	v_add_f32_dpp v63, v63, v63 quad_perm:[2,3,0,1] row_mask:0xf bank_mask:0xf bound_ctrl:1
	v_sub_f32_e32 v116, v68, v62
	v_sub_f32_e32 v223, v112, v63
	v_fma_f32 v120, -v103, v116, v223
	v_cndmask_b32_e64 v54, v54, v116, s[10:11]
	v_cndmask_b32_e64 v55, v55, v120, s[10:11]
.Lfs_row28:
	ds_read_b128 v[122:125], v14 offset:15776
	ds_read_b128 v[126:129], v14 offset:15840
	ds_read_b128 v[130:133], v14 offset:15904
	ds_read_b128 v[38:41], v14 offset:15968
	ds_read_b128 v[42:45], v14 offset:16032
	ds_read_b128 v[46:49], v14 offset:16096
	ds_read_b128 v[102:105], v14 offset:16160
	ds_read_b128 v[242:245], v14 offset:16224
	v_cmp_eq_u32_e64 s[12:13], 56, v12
	v_cmp_eq_u32_e64 s[14:15], 57, v12
	s_waitcnt lgkmcnt(8)
	v_pk_fma_f32 v[62:63], v[70:71], v[2:3], 0 op_sel_hi:[1,0,0]
	v_pk_fma_f32 v[66:67], v[72:73], v[2:3], 0 op_sel:[0,1,0] op_sel_hi:[1,1,0]
	v_cndmask_b32_e64 v68, 0, 1.0, s[12:13]
	v_cndmask_b32_e64 v112, 0, 1.0, s[14:15]
	v_pk_fma_f32 v[106:107], v[74:75], v[4:5], 0 op_sel_hi:[1,0,0]
	v_pk_fma_f32 v[110:111], v[76:77], v[4:5], 0 op_sel:[0,1,0] op_sel_hi:[1,1,0]
	v_pk_fma_f32 v[62:63], v[78:79], v[8:9], v[62:63] op_sel_hi:[1,0,1]
	v_pk_fma_f32 v[66:67], v[80:81], v[8:9], v[66:67] op_sel:[0,1,0] op_sel_hi:[1,1,1]
	v_pk_fma_f32 v[106:107], v[82:83], v[10:11], v[106:107] op_sel_hi:[1,0,1]
	v_pk_fma_f32 v[110:111], v[84:85], v[10:11], v[110:111] op_sel:[0,1,0] op_sel_hi:[1,1,1]
	v_pk_fma_f32 v[62:63], v[86:87], v[18:19], v[62:63] op_sel_hi:[1,0,1]
	v_pk_fma_f32 v[66:67], v[88:89], v[18:19], v[66:67] op_sel:[0,1,0] op_sel_hi:[1,1,1]
	v_pk_fma_f32 v[106:107], v[90:91], v[50:51], v[106:107] op_sel_hi:[1,0,1]
	v_pk_fma_f32 v[110:111], v[92:93], v[50:51], v[110:111] op_sel:[0,1,0] op_sel_hi:[1,1,1]
	v_pk_fma_f32 v[62:63], v[98:99], v[58:59], v[62:63] op_sel_hi:[1,0,1]
	v_pk_fma_f32 v[66:67], v[100:101], v[58:59], v[66:67] op_sel:[0,1,0] op_sel_hi:[1,1,1]
	v_pk_fma_f32 v[106:107], v[94:95], v[54:55], v[106:107] op_sel_hi:[1,0,1]
	v_pk_fma_f32 v[110:111], v[96:97], v[54:55], v[110:111] op_sel:[0,1,0] op_sel_hi:[1,1,1]
	v_pk_add_f32 v[62:63], v[62:63], v[106:107]
	v_pk_add_f32 v[66:67], v[66:67], v[110:111]
	v_pk_add_f32 v[62:63], v[62:63], v[66:67]
	s_nop 1
	v_add_f32_dpp v62, v62, v62 quad_perm:[1,0,3,2] row_mask:0xf bank_mask:0xf bound_ctrl:1
	v_add_f32_dpp v63, v63, v63 quad_perm:[1,0,3,2] row_mask:0xf bank_mask:0xf bound_ctrl:1
	s_nop 0
	v_add_f32_dpp v62, v62, v62 quad_perm:[2,3,0,1] row_mask:0xf bank_mask:0xf bound_ctrl:1
	v_add_f32_dpp v63, v63, v63 quad_perm:[2,3,0,1] row_mask:0xf bank_mask:0xf bound_ctrl:1
	v_sub_f32_e32 v116, v68, v62
	v_sub_f32_e32 v223, v112, v63
	v_fma_f32 v120, -v99, v116, v223
	v_cndmask_b32_e64 v58, v58, v116, s[4:5]
	v_cndmask_b32_e64 v59, v59, v120, s[4:5]
; #define LAS __attribute__((address_space(3)))
;     ...
; #pragma unroll
;         for (int ip = 0; ip < 32; ++ip) {
;             const int i0 = 2 * ip;
;             f32x4 rv[32];
; #pragma unroll
;             for (int jp = 0; jp <= ip; ++jp) rv[jp] = *(const LAS f32x4*)(Ad + ip * 136 + 4 * jp);
;             asm volatile("" : "+v"(lane_o) :: "memory");
;             f32x2_ a0 = {0.f, 0.f}, a1 = {0.f, 0.f}, a2 = {0.f, 0.f}, a3 = {0.f, 0.f};
; #pragma unroll
;             for (int jp = 0; jp < ip; ++jp) {
;                 const f32x2_ ta = {tr[2 * jp], tr[2 * jp]}, tb = {tr[2 * jp + 1], tr[2 * jp + 1]};
;                 const f32x2_ va = {rv[jp][0], rv[jp][1]}, vb = {rv[jp][2], rv[jp][3]};
;                 if (jp & 1) { a2 += va * ta; a3 += vb * tb; } else { a0 += va * ta; a1 += vb * tb; }
;             }
;             const f32x2_ sum = (a0 + a1) + (a2 + a3);
;             const float t0 = (lane_o == i0 ? 1.f : 0.f) - sum[0];
;             tr[i0] = t0;
;             tr[i0 + 1] = (lane_o == i0 + 1 ? 1.f : 0.f) - sum[1] - rv[ip][1] * t0;
;         }
.Lfs_row29:
	ds_read_b128 v[70:73], v14 offset:16320
	ds_read_b128 v[74:77], v14 offset:16384
	ds_read_b128 v[78:81], v14 offset:16448
	ds_read_b128 v[82:85], v14 offset:16512
	ds_read_b128 v[86:89], v14 offset:16576
	ds_read_b128 v[90:93], v14 offset:16640
	ds_read_b128 v[94:97], v14 offset:16704
	ds_read_b128 v[98:101], v14 offset:16768
	v_cmp_eq_u32_e64 s[12:13], 58, v12
	v_cmp_eq_u32_e64 s[14:15], 59, v12
	s_waitcnt lgkmcnt(8)
	v_pk_fma_f32 v[62:63], v[122:123], v[2:3], 0 op_sel_hi:[1,0,0]
	v_pk_fma_f32 v[66:67], v[124:125], v[2:3], 0 op_sel:[0,1,0] op_sel_hi:[1,1,0]
	v_cndmask_b32_e64 v68, 0, 1.0, s[12:13]
	v_cndmask_b32_e64 v112, 0, 1.0, s[14:15]
	v_pk_fma_f32 v[106:107], v[126:127], v[4:5], 0 op_sel_hi:[1,0,0]
	v_pk_fma_f32 v[110:111], v[128:129], v[4:5], 0 op_sel:[0,1,0] op_sel_hi:[1,1,0]
	v_pk_fma_f32 v[62:63], v[130:131], v[8:9], v[62:63] op_sel_hi:[1,0,1]
	v_pk_fma_f32 v[66:67], v[132:133], v[8:9], v[66:67] op_sel:[0,1,0] op_sel_hi:[1,1,1]
	v_pk_fma_f32 v[106:107], v[38:39], v[10:11], v[106:107] op_sel_hi:[1,0,1]
	v_pk_fma_f32 v[110:111], v[40:41], v[10:11], v[110:111] op_sel:[0,1,0] op_sel_hi:[1,1,1]
	v_pk_fma_f32 v[62:63], v[42:43], v[18:19], v[62:63] op_sel_hi:[1,0,1]
	v_pk_fma_f32 v[66:67], v[44:45], v[18:19], v[66:67] op_sel:[0,1,0] op_sel_hi:[1,1,1]
	v_pk_fma_f32 v[106:107], v[46:47], v[50:51], v[106:107] op_sel_hi:[1,0,1]
	v_pk_fma_f32 v[110:111], v[48:49], v[50:51], v[110:111] op_sel:[0,1,0] op_sel_hi:[1,1,1]
	v_pk_fma_f32 v[62:63], v[102:103], v[54:55], v[62:63] op_sel_hi:[1,0,1]
	v_pk_fma_f32 v[66:67], v[104:105], v[54:55], v[66:67] op_sel:[0,1,0] op_sel_hi:[1,1,1]
	v_pk_fma_f32 v[106:107], v[242:243], v[58:59], v[106:107] op_sel_hi:[1,0,1]
	v_pk_fma_f32 v[110:111], v[244:245], v[58:59], v[110:111] op_sel:[0,1,0] op_sel_hi:[1,1,1]
	v_pk_add_f32 v[62:63], v[62:63], v[106:107]
	v_pk_add_f32 v[66:67], v[66:67], v[110:111]
	v_pk_add_f32 v[62:63], v[62:63], v[66:67]
	s_nop 1
	v_add_f32_dpp v62, v62, v62 quad_perm:[1,0,3,2] row_mask:0xf bank_mask:0xf bound_ctrl:1
	v_add_f32_dpp v63, v63, v63 quad_perm:[1,0,3,2] row_mask:0xf bank_mask:0xf bound_ctrl:1
	s_nop 0
	v_add_f32_dpp v62, v62, v62 quad_perm:[2,3,0,1] row_mask:0xf bank_mask:0xf bound_ctrl:1
	v_add_f32_dpp v63, v63, v63 quad_perm:[2,3,0,1] row_mask:0xf bank_mask:0xf bound_ctrl:1
	v_sub_f32_e32 v116, v68, v62
	v_sub_f32_e32 v223, v112, v63
	v_fma_f32 v120, -v243, v116, v223
	v_cndmask_b32_e64 v58, v58, v116, s[6:7]
	v_cndmask_b32_e64 v59, v59, v120, s[6:7]
.Lfs_row30:
	ds_read_b128 v[122:125], v14 offset:16864
	ds_read_b128 v[126:129], v14 offset:16928
	ds_read_b128 v[130:133], v14 offset:16992
	ds_read_b128 v[38:41], v14 offset:17056
	ds_read_b128 v[42:45], v14 offset:17120
	ds_read_b128 v[46:49], v14 offset:17184
	ds_read_b128 v[102:105], v14 offset:17248
	ds_read_b128 v[242:245], v14 offset:17312
	v_cmp_eq_u32_e64 s[12:13], 60, v12
	v_cmp_eq_u32_e64 s[14:15], 61, v12
	s_waitcnt lgkmcnt(8)
	v_pk_fma_f32 v[62:63], v[70:71], v[2:3], 0 op_sel_hi:[1,0,0]
	v_pk_fma_f32 v[66:67], v[72:73], v[2:3], 0 op_sel:[0,1,0] op_sel_hi:[1,1,0]
	v_cndmask_b32_e64 v68, 0, 1.0, s[12:13]
	v_cndmask_b32_e64 v112, 0, 1.0, s[14:15]
	v_pk_fma_f32 v[106:107], v[74:75], v[4:5], 0 op_sel_hi:[1,0,0]
	v_pk_fma_f32 v[110:111], v[76:77], v[4:5], 0 op_sel:[0,1,0] op_sel_hi:[1,1,0]
	v_pk_fma_f32 v[62:63], v[78:79], v[8:9], v[62:63] op_sel_hi:[1,0,1]
	v_pk_fma_f32 v[66:67], v[80:81], v[8:9], v[66:67] op_sel:[0,1,0] op_sel_hi:[1,1,1]
	v_pk_fma_f32 v[106:107], v[82:83], v[10:11], v[106:107] op_sel_hi:[1,0,1]
	v_pk_fma_f32 v[110:111], v[84:85], v[10:11], v[110:111] op_sel:[0,1,0] op_sel_hi:[1,1,1]
	v_pk_fma_f32 v[62:63], v[86:87], v[18:19], v[62:63] op_sel_hi:[1,0,1]
	v_pk_fma_f32 v[66:67], v[88:89], v[18:19], v[66:67] op_sel:[0,1,0] op_sel_hi:[1,1,1]
	v_pk_fma_f32 v[106:107], v[90:91], v[50:51], v[106:107] op_sel_hi:[1,0,1]
	v_pk_fma_f32 v[110:111], v[92:93], v[50:51], v[110:111] op_sel:[0,1,0] op_sel_hi:[1,1,1]
	v_pk_fma_f32 v[62:63], v[94:95], v[54:55], v[62:63] op_sel_hi:[1,0,1]
	v_pk_fma_f32 v[66:67], v[96:97], v[54:55], v[66:67] op_sel:[0,1,0] op_sel_hi:[1,1,1]
	v_pk_fma_f32 v[106:107], v[98:99], v[58:59], v[106:107] op_sel_hi:[1,0,1]
	v_pk_fma_f32 v[110:111], v[100:101], v[58:59], v[110:111] op_sel:[0,1,0] op_sel_hi:[1,1,1]
	v_pk_add_f32 v[62:63], v[62:63], v[106:107]
	v_pk_add_f32 v[66:67], v[66:67], v[110:111]
	v_pk_add_f32 v[62:63], v[62:63], v[66:67]
	s_nop 1
	v_add_f32_dpp v62, v62, v62 quad_perm:[1,0,3,2] row_mask:0xf bank_mask:0xf bound_ctrl:1
	v_add_f32_dpp v63, v63, v63 quad_perm:[1,0,3,2] row_mask:0xf bank_mask:0xf bound_ctrl:1
	s_nop 0
	v_add_f32_dpp v62, v62, v62 quad_perm:[2,3,0,1] row_mask:0xf bank_mask:0xf bound_ctrl:1
	v_add_f32_dpp v63, v63, v63 quad_perm:[2,3,0,1] row_mask:0xf bank_mask:0xf bound_ctrl:1
	v_sub_f32_e32 v116, v68, v62
	v_sub_f32_e32 v223, v112, v63
	v_fma_f32 v120, -v99, v116, v223
	v_cndmask_b32_e64 v58, v58, v116, s[8:9]
	v_cndmask_b32_e64 v59, v59, v120, s[8:9]
; #define LAS __attribute__((address_space(3)))
; __device__ __forceinline__ unsigned f2bf(float f) { return pk2(f, 0.f) & 0xffffu; }
; __device__ __forceinline__ float fexp(float x) { return __builtin_amdgcn_exp2f(x * 1.4426950408889634f); }
;     ...
; #pragma unroll
;         for (int ip = 0; ip < 32; ++ip) {
;             const int i0 = 2 * ip;
;             f32x4 rv[32];
; #pragma unroll
;             for (int jp = 0; jp <= ip; ++jp) rv[jp] = *(const LAS f32x4*)(Ad + ip * 136 + 4 * jp);
;             asm volatile("" : "+v"(lane_o) :: "memory");
;             f32x2_ a0 = {0.f, 0.f}, a1 = {0.f, 0.f}, a2 = {0.f, 0.f}, a3 = {0.f, 0.f};
; #pragma unroll
;             for (int jp = 0; jp < ip; ++jp) {
;                 const f32x2_ ta = {tr[2 * jp], tr[2 * jp]}, tb = {tr[2 * jp + 1], tr[2 * jp + 1]};
;                 const f32x2_ va = {rv[jp][0], rv[jp][1]}, vb = {rv[jp][2], rv[jp][3]};
;                 if (jp & 1) { a2 += va * ta; a3 += vb * tb; } else { a0 += va * ta; a1 += vb * tb; }
;             }
;             const f32x2_ sum = (a0 + a1) + (a2 + a3);
;             const float t0 = (lane_o == i0 ? 1.f : 0.f) - sum[0];
;             tr[i0] = t0;
;             tr[i0 + 1] = (lane_o == i0 + 1 ? 1.f : 0.f) - sum[1] - rv[ip][1] * t0;
;         }
;         const int pb = d ? 63 - lane : lane; const float sb = bS[d * 64 + pb], sbe = sb * fexp(gcS[d * 64 + pb]);
;         LAS bf16_t* T0 = Tb + d * 9216; LAS bf16_t* T1 = T0 + 4608;
; #pragma unroll
;         for (int i = 0; i < 64; ++i) { const int pa = d ? 63 - i : i; T0[pa * 72 + pb] = (bf16_t)f2bf(tr[i] * sb); T1[pa * 72 + pb] = (bf16_t)f2bf(tr[i] * sbe); }
.Lfs_row31:
	v_cmp_eq_u32_e64 s[12:13], 62, v12
	v_cmp_eq_u32_e64 s[14:15], 63, v12
	s_waitcnt lgkmcnt(0)
	v_pk_fma_f32 v[62:63], v[122:123], v[2:3], 0 op_sel_hi:[1,0,0]
	v_pk_fma_f32 v[66:67], v[124:125], v[2:3], 0 op_sel:[0,1,0] op_sel_hi:[1,1,0]
	v_cndmask_b32_e64 v68, 0, 1.0, s[12:13]
	v_cndmask_b32_e64 v112, 0, 1.0, s[14:15]
	v_pk_fma_f32 v[106:107], v[126:127], v[4:5], 0 op_sel_hi:[1,0,0]
	v_pk_fma_f32 v[110:111], v[128:129], v[4:5], 0 op_sel:[0,1,0] op_sel_hi:[1,1,0]
	v_pk_fma_f32 v[62:63], v[130:131], v[8:9], v[62:63] op_sel_hi:[1,0,1]
	v_pk_fma_f32 v[66:67], v[132:133], v[8:9], v[66:67] op_sel:[0,1,0] op_sel_hi:[1,1,1]
	v_pk_fma_f32 v[106:107], v[38:39], v[10:11], v[106:107] op_sel_hi:[1,0,1]
	v_pk_fma_f32 v[110:111], v[40:41], v[10:11], v[110:111] op_sel:[0,1,0] op_sel_hi:[1,1,1]
	v_pk_fma_f32 v[62:63], v[42:43], v[18:19], v[62:63] op_sel_hi:[1,0,1]
	v_pk_fma_f32 v[66:67], v[44:45], v[18:19], v[66:67] op_sel:[0,1,0] op_sel_hi:[1,1,1]
	v_pk_fma_f32 v[106:107], v[46:47], v[50:51], v[106:107] op_sel_hi:[1,0,1]
	v_pk_fma_f32 v[110:111], v[48:49], v[50:51], v[110:111] op_sel:[0,1,0] op_sel_hi:[1,1,1]
	v_pk_fma_f32 v[62:63], v[102:103], v[54:55], v[62:63] op_sel_hi:[1,0,1]
	v_pk_fma_f32 v[66:67], v[104:105], v[54:55], v[66:67] op_sel:[0,1,0] op_sel_hi:[1,1,1]
	v_pk_fma_f32 v[106:107], v[242:243], v[58:59], v[106:107] op_sel_hi:[1,0,1]
	v_pk_fma_f32 v[110:111], v[244:245], v[58:59], v[110:111] op_sel:[0,1,0] op_sel_hi:[1,1,1]
	v_pk_add_f32 v[62:63], v[62:63], v[106:107]
	v_pk_add_f32 v[66:67], v[66:67], v[110:111]
	v_pk_add_f32 v[62:63], v[62:63], v[66:67]
	s_nop 1
	v_add_f32_dpp v62, v62, v62 quad_perm:[1,0,3,2] row_mask:0xf bank_mask:0xf bound_ctrl:1
	v_add_f32_dpp v63, v63, v63 quad_perm:[1,0,3,2] row_mask:0xf bank_mask:0xf bound_ctrl:1
	s_nop 0
	v_add_f32_dpp v62, v62, v62 quad_perm:[2,3,0,1] row_mask:0xf bank_mask:0xf bound_ctrl:1
	v_add_f32_dpp v63, v63, v63 quad_perm:[2,3,0,1] row_mask:0xf bank_mask:0xf bound_ctrl:1
	v_sub_f32_e32 v116, v68, v62
	v_sub_f32_e32 v223, v112, v63
	v_fma_f32 v120, -v243, v116, v223
	v_cndmask_b32_e64 v58, v58, v116, s[10:11]
	v_cndmask_b32_e64 v59, v59, v120, s[10:11]
	s_cmp_eq_u32 s1, 0
	s_cbranch_scc0 .Lfs_out1
	v_pk_mul_f32 v[114:115], v[2:3], v[56:57] op_sel_hi:[1,0]
	v_pk_mul_f32 v[118:119], v[2:3], v[60:61] op_sel_hi:[1,0]
	v_cvt_pk_bf16_f32 v174, v114, v115
	v_cvt_pk_bf16_f32 v175, v118, v119
	ds_write_b16 v64, v174
	ds_write_b16_d16_hi v64, v174 offset:144
	ds_write_b16 v64, v175 offset:9216
	ds_write_b16_d16_hi v64, v175 offset:9360
	v_pk_mul_f32 v[114:115], v[4:5], v[56:57] op_sel_hi:[1,0]
	v_pk_mul_f32 v[118:119], v[4:5], v[60:61] op_sel_hi:[1,0]
	v_cvt_pk_bf16_f32 v174, v114, v115
	v_cvt_pk_bf16_f32 v175, v118, v119
	ds_write_b16 v64, v174 offset:1152
	ds_write_b16_d16_hi v64, v174 offset:1296
	ds_write_b16 v64, v175 offset:10368
	ds_write_b16_d16_hi v64, v175 offset:10512
	v_pk_mul_f32 v[114:115], v[8:9], v[56:57] op_sel_hi:[1,0]
	v_pk_mul_f32 v[118:119], v[8:9], v[60:61] op_sel_hi:[1,0]
	v_cvt_pk_bf16_f32 v174, v114, v115
	v_cvt_pk_bf16_f32 v175, v118, v119
	ds_write_b16 v64, v174 offset:2304
	ds_write_b16_d16_hi v64, v174 offset:2448
	ds_write_b16 v64, v175 offset:11520
	ds_write_b16_d16_hi v64, v175 offset:11664
	v_pk_mul_f32 v[114:115], v[10:11], v[56:57] op_sel_hi:[1,0]
	v_pk_mul_f32 v[118:119], v[10:11], v[60:61] op_sel_hi:[1,0]
	v_cvt_pk_bf16_f32 v174, v114, v115
	v_cvt_pk_bf16_f32 v175, v118, v119
	ds_write_b16 v64, v174 offset:3456
	ds_write_b16_d16_hi v64, v174 offset:3600
	ds_write_b16 v64, v175 offset:12672
	ds_write_b16_d16_hi v64, v175 offset:12816
	v_pk_mul_f32 v[114:115], v[18:19], v[56:57] op_sel_hi:[1,0]
	v_pk_mul_f32 v[118:119], v[18:19], v[60:61] op_sel_hi:[1,0]
	v_cvt_pk_bf16_f32 v174, v114, v115
	v_cvt_pk_bf16_f32 v175, v118, v119
	ds_write_b16 v64, v174 offset:4608
	ds_write_b16_d16_hi v64, v174 offset:4752
	ds_write_b16 v64, v175 offset:13824
	ds_write_b16_d16_hi v64, v175 offset:13968
	v_pk_mul_f32 v[114:115], v[50:51], v[56:57] op_sel_hi:[1,0]
	v_pk_mul_f32 v[118:119], v[50:51], v[60:61] op_sel_hi:[1,0]
	v_cvt_pk_bf16_f32 v174, v114, v115
	v_cvt_pk_bf16_f32 v175, v118, v119
	ds_write_b16 v64, v174 offset:5760
	ds_write_b16_d16_hi v64, v174 offset:5904
	ds_write_b16 v64, v175 offset:14976
	ds_write_b16_d16_hi v64, v175 offset:15120
	v_pk_mul_f32 v[114:115], v[54:55], v[56:57] op_sel_hi:[1,0]
	v_pk_mul_f32 v[118:119], v[54:55], v[60:61] op_sel_hi:[1,0]
	v_cvt_pk_bf16_f32 v174, v114, v115
	v_cvt_pk_bf16_f32 v175, v118, v119
	ds_write_b16 v64, v174 offset:6912
	ds_write_b16_d16_hi v64, v174 offset:7056
	ds_write_b16 v64, v175 offset:16128
	ds_write_b16_d16_hi v64, v175 offset:16272
	v_pk_mul_f32 v[114:115], v[58:59], v[56:57] op_sel_hi:[1,0]
	v_pk_mul_f32 v[118:119], v[58:59], v[60:61] op_sel_hi:[1,0]
	v_cvt_pk_bf16_f32 v174, v114, v115
	v_cvt_pk_bf16_f32 v175, v118, v119
	ds_write_b16 v64, v174 offset:8064
	ds_write_b16_d16_hi v64, v174 offset:8208
	ds_write_b16 v64, v175 offset:17280
	ds_write_b16_d16_hi v64, v175 offset:17424
	s_branch .Lfs_done
; #define LAS __attribute__((address_space(3)))
; __device__ __forceinline__ unsigned f2bf(float f) { return pk2(f, 0.f) & 0xffffu; }
; __device__ __forceinline__ float fexp(float x) { return __builtin_amdgcn_exp2f(x * 1.4426950408889634f); }
; __device__ __forceinline__ void gdn_preload(const Frame& F, int u, int t, GdnPre& P) {
;     const int b = u / 144, h = (u / 36) & 3, cidx = u % 36, row0 = chunk_row0(b, cidx);
;     const int seg_lo = cidx < 4 ? MLAT + b * CTXL : b * SEQ, seg_hi = seg_lo + (cidx < 4 ? CTXL : SEQ);
;     if (t < 384) {
;         const int pair = t % 96, rg = t / 96, c0 = 2 * pair, part = c0 >> 6, d0 = c0 & 63, zcol = part * 256 + h * 64 + d0;
;         const int rbase = row0 + rg * 16 - 2; const bf16_t* zc = F.Z + zcol;
; #pragma unroll
;         for (int rr = 0; rr < 20; ++rr) { int row = rbase + rr; row = row < seg_lo ? seg_lo : (row >= seg_hi ? seg_hi - 1 : row); P.raw[rr] = *(const unsigned*)(zc + (size_t)row * ZW); }
;     ...
;         const int pb = d ? 63 - lane : lane; const float sb = bS[d * 64 + pb], sbe = sb * fexp(gcS[d * 64 + pb]);
;         LAS bf16_t* T0 = Tb + d * 9216; LAS bf16_t* T1 = T0 + 4608;
; #pragma unroll
;         for (int i = 0; i < 64; ++i) { const int pa = d ? 63 - i : i; T0[pa * 72 + pb] = (bf16_t)f2bf(tr[i] * sb); T1[pa * 72 + pb] = (bf16_t)f2bf(tr[i] * sbe); }
.Lfs_out1:
	v_pk_mul_f32 v[114:115], v[2:3], v[56:57] op_sel_hi:[1,0]
	v_pk_mul_f32 v[118:119], v[2:3], v[60:61] op_sel_hi:[1,0]
	v_cvt_pk_bf16_f32 v174, v114, v115
	v_cvt_pk_bf16_f32 v175, v118, v119
	ds_write_b16 v64, v174 offset:8208
	ds_write_b16_d16_hi v64, v174 offset:8064
	ds_write_b16 v64, v175 offset:17424
	ds_write_b16_d16_hi v64, v175 offset:17280
	v_pk_mul_f32 v[114:115], v[4:5], v[56:57] op_sel_hi:[1,0]
	v_pk_mul_f32 v[118:119], v[4:5], v[60:61] op_sel_hi:[1,0]
	v_cvt_pk_bf16_f32 v174, v114, v115
	v_cvt_pk_bf16_f32 v175, v118, v119
	ds_write_b16 v64, v174 offset:7056
	ds_write_b16_d16_hi v64, v174 offset:6912
	ds_write_b16 v64, v175 offset:16272
	ds_write_b16_d16_hi v64, v175 offset:16128
	v_pk_mul_f32 v[114:115], v[8:9], v[56:57] op_sel_hi:[1,0]
	v_pk_mul_f32 v[118:119], v[8:9], v[60:61] op_sel_hi:[1,0]
	v_cvt_pk_bf16_f32 v174, v114, v115
	v_cvt_pk_bf16_f32 v175, v118, v119
	ds_write_b16 v64, v174 offset:5904
	ds_write_b16_d16_hi v64, v174 offset:5760
	ds_write_b16 v64, v175 offset:15120
	ds_write_b16_d16_hi v64, v175 offset:14976
	v_pk_mul_f32 v[114:115], v[10:11], v[56:57] op_sel_hi:[1,0]
	v_pk_mul_f32 v[118:119], v[10:11], v[60:61] op_sel_hi:[1,0]
	v_cvt_pk_bf16_f32 v174, v114, v115
	v_cvt_pk_bf16_f32 v175, v118, v119
	ds_write_b16 v64, v174 offset:4752
	ds_write_b16_d16_hi v64, v174 offset:4608
	ds_write_b16 v64, v175 offset:13968
	ds_write_b16_d16_hi v64, v175 offset:13824
	v_pk_mul_f32 v[114:115], v[18:19], v[56:57] op_sel_hi:[1,0]
	v_pk_mul_f32 v[118:119], v[18:19], v[60:61] op_sel_hi:[1,0]
	v_cvt_pk_bf16_f32 v174, v114, v115
	v_cvt_pk_bf16_f32 v175, v118, v119
	ds_write_b16 v64, v174 offset:3600
	ds_write_b16_d16_hi v64, v174 offset:3456
	ds_write_b16 v64, v175 offset:12816
	ds_write_b16_d16_hi v64, v175 offset:12672
	v_pk_mul_f32 v[114:115], v[50:51], v[56:57] op_sel_hi:[1,0]
	v_pk_mul_f32 v[118:119], v[50:51], v[60:61] op_sel_hi:[1,0]
	v_cvt_pk_bf16_f32 v174, v114, v115
	v_cvt_pk_bf16_f32 v175, v118, v119
	ds_write_b16 v64, v174 offset:2448
	ds_write_b16_d16_hi v64, v174 offset:2304
	ds_write_b16 v64, v175 offset:11664
	ds_write_b16_d16_hi v64, v175 offset:11520
	v_pk_mul_f32 v[114:115], v[54:55], v[56:57] op_sel_hi:[1,0]
	v_pk_mul_f32 v[118:119], v[54:55], v[60:61] op_sel_hi:[1,0]
	v_cvt_pk_bf16_f32 v174, v114, v115
	v_cvt_pk_bf16_f32 v175, v118, v119
	ds_write_b16 v64, v174 offset:1296
	ds_write_b16_d16_hi v64, v174 offset:1152
	ds_write_b16 v64, v175 offset:10512
	ds_write_b16_d16_hi v64, v175 offset:10368
	v_pk_mul_f32 v[114:115], v[58:59], v[56:57] op_sel_hi:[1,0]
	v_pk_mul_f32 v[118:119], v[58:59], v[60:61] op_sel_hi:[1,0]
	v_cvt_pk_bf16_f32 v174, v114, v115
	v_cvt_pk_bf16_f32 v175, v118, v119
	ds_write_b16 v64, v174 offset:144
	ds_write_b16_d16_hi v64, v174
	ds_write_b16 v64, v175 offset:9360
	ds_write_b16_d16_hi v64, v175 offset:9216
.Lfs_done:
	s_waitcnt lgkmcnt(0)
.LBB0_644:
	s_cmp_gt_i32 s28, 3
	s_cselect_b32 s6, s76, s77
	s_add_i32 s1, 0, 0xe000
	s_cmp_gt_i32 s28, 3
	s_cselect_b32 s7, s1, s2
	s_add_i32 s3, 0, 0x4800
	s_cmp_gt_i32 s28, 3
	v_readlane_b32 s4, v253, 56
	s_cselect_b32 s8, 0x2400, 0
	s_cselect_b32 s12, s3, s4
	s_add_i32 s4, s34, 0x100
	s_cmpk_gt_i32 s34, 0x37f
	s_cselect_b64 s[10:11], -1, 0
	s_cmpk_lt_i32 s34, 0x380
	s_cselect_b32 s13, s4, -1
	s_lshl_b32 s14, s28, 4
	s_and_b32 s14, s14, 48
	s_add_i32 s8, s8, 0
	s_mul_i32 s15, s14, 0x90
	s_add_i32 s8, s8, s15
	s_add_i32 s8, s8, 0x12800
	v_or_b32_e32 v0, s14, v17
	v_add3_u32 v63, s8, v113, v117
	v_lshl_add_u32 v110, v0, 2, 0
	v_lshlrev_b32_e32 v0, 1, v0
	s_ashr_i32 s8, s28, 1
	v_add_u32_e32 v4, s7, v0
	v_add_u32_e32 v0, s6, v0
	s_lshl_b32 s6, s8, 12
	s_ashr_i32 s7, s6, 31
	s_lshl_b32 s5, s34, 1
	v_add3_u32 v108, s12, v113, v117
	s_lshl_b64 s[6:7], s[6:7], 1
	v_readlane_b32 s12, v254, 59
	s_add_u32 s6, s12, s6
	v_readlane_b32 s12, v254, 60
	s_addc_u32 s7, s12, s7
	s_cmp_lt_u32 s28, 2
	s_cselect_b64 s[40:41], -1, 0
	s_cmp_eq_u32 s8, 1
	s_cselect_b64 s[28:29], -1, 0
	s_cmp_eq_u32 s8, 2
	s_cselect_b64 s[30:31], -1, 0
	s_and_b32 s12, s0, 8
	s_cmp_lt_i32 s13, 0
	s_cselect_b32 s0, s34, s13
	s_mul_hi_i32 s8, s0, 0x38e38e39
	s_ashr_i32 s13, s8, 5
	s_lshr_b32 s14, s8, 31
	s_ashr_i32 s8, s8, 3
	s_add_i32 s8, s8, s14
	s_add_i32 s13, s13, s14
	s_and_b32 s14, s8, 3
	s_mul_i32 s8, s8, 36
	s_or_b32 s49, s12, 6
	s_sub_i32 s0, s0, s8
	s_lshl_b32 s15, s13, 11
	s_lshl_b32 s8, s13, 8
	s_or_b64 s[34:35], s[40:41], s[30:31]
	s_lshl_b32 s42, s49, 2
	s_lshl_b32 s33, s0, 6
	s_add_i32 s44, s15, 0xffffff00
	s_add_i32 s13, s8, 0x4000
	s_lshl_b32 s8, s14, 6
	s_xor_b64 s[36:37], s[34:35], -1
	s_lshl_b32 s45, s12, 3
	s_or_b32 s48, s12, 4
	s_and_b32 s50, s42, 48
	v_mul_u32_u24_e32 v9, 0x48, v109
	s_cmp_lt_i32 s0, 4
	v_and_b32_e32 v2, 0xffffffc, v61
	v_lshlrev_b32_e32 v9, 1, v9
	v_or_b32_e32 v2, s14, v2
	v_add_u32_e32 v11, 0x900, v9
	s_cselect_b32 s14, s13, s15
	s_cselect_b32 s13, s13, s44
	s_movk_i32 s15, 0x7ff
	v_add_u32_e32 v6, v69, v65
	v_add_u32_e32 v61, v4, v9
	v_add_u32_e32 v111, v0, v9
	v_add_u32_e32 v112, v4, v11
	v_add_u32_e32 v114, v0, v11
	v_add_u32_e32 v11, 0x1200, v9
	v_add_u32_e32 v9, 0x1b00, v9
	s_cselect_b32 s15, 0xff, s15
	s_add_i32 s13, s13, s33
	s_movk_i32 s0, 0x60
	v_add_u32_e32 v115, v4, v11
	v_add_u32_e32 v118, v4, v9
	v_lshl_add_u32 v4, v6, 4, s13
	v_lshlrev_b32_e32 v5, 1, v2
	v_mul_lo_u32 v2, v6, s0
; #define LAS __attribute__((address_space(3)))
; __device__ __forceinline__ void gdn_preload(const Frame& F, int u, int t, GdnPre& P) {
;     const int b = u / 144, h = (u / 36) & 3, cidx = u % 36, row0 = chunk_row0(b, cidx);
;     const int seg_lo = cidx < 4 ? MLAT + b * CTXL : b * SEQ, seg_hi = seg_lo + (cidx < 4 ? CTXL : SEQ);
;     if (t < 384) {
;         const int pair = t % 96, rg = t / 96, c0 = 2 * pair, part = c0 >> 6, d0 = c0 & 63, zcol = part * 256 + h * 64 + d0;
;         const int rbase = row0 + rg * 16 - 2; const bf16_t* zc = F.Z + zcol;
; #pragma unroll
;         for (int rr = 0; rr < 20; ++rr) { int row = rbase + rr; row = row < seg_lo ? seg_lo : (row >= seg_hi ? seg_hi - 1 : row); P.raw[rr] = *(const unsigned*)(zc + (size_t)row * ZW); }
;     ...
;     for (int d = 0; d < 2; ++d) {
;         const int ud = u * 2 + d; const float tot = totS[d];
;         const LAS bf16_t* T0 = Tb + d * 9216; const LAS bf16_t* T1 = T0 + 4608; const LAS bf16_t* Ad = At + d * 4608;
;         {
;             const bool isw = w >= 4; const LAS bf16_t* Aop = isw ? T1 : T0; const LAS bf16_t* Bop = isw ? Kt : Vt;
;             LAS bf16_t* o0 = isw ? WT : UT; LAS bf16_t* o1 = isw ? WTd : UTd;
; #pragma unroll
;             for (int k4 = 0; k4 < 4; ++k4) { const int tt = (w & 3) * 4 + k4, mt = tt >> 2, nt = tt & 3;
;                 f32x4 acc = {0.f, 0.f, 0.f, 0.f}; acc = mma_ll<2>(Aop + mt * 16 * 72, 72, Bop + nt * 16 * 72, 72, acc, lane);
;                 const int n = nt * 16 + lr, m0 = mt * 16 + 4 * lq; f32x4 dv;
; #pragma unroll
;                 for (int i = 0; i < 4; ++i) dv[i] = acc[i] * gS[d * 64 + m0 + i];
;                 *(LAS v2u*)(o0 + n * 72 + m0) = pack4(acc); *(LAS v2u*)(o1 + n * 72 + m0) = pack4(dv); }
;         }
;         __syncthreads();
;         if (stop == 6) { __syncthreads(); continue; }
;         {
;             const int prod = w >> 1; bf16_t* gout = PGo + (size_t)ud * 16384 + prod * 4096;
;             const LAS bf16_t* Aop = prod == 0 ? WTd : prod == 1 ? Kt : prod == 2 ? WT : Ad;
;             const LAS bf16_t* Bop = prod == 0 ? Kt : prod == 1 ? UTd : prod == 2 ? Ad : UT;
;             v2u res[8];
; #pragma unroll
;             for (int k8 = 0; k8 < 8; ++k8) { const int tt = (w & 1) * 8 + k8, mt = tt >> 2, nt = tt & 3;
;                 f32x4 acc = {0.f, 0.f, 0.f, 0.f}; acc = mma_ll<2>(Aop + mt * 16 * 72, 72, Bop + nt * 16 * 72, 72, acc, lane);
	v_or_b32_e32 v10, 16, v109
	v_add_u32_e32 v6, -2, v4
	s_add_i32 s15, s15, s14
	v_mad_u32_u24 v122, v10, s92, 0
	v_min_i32_e32 v10, s15, v6
	v_mov_b32_e32 v12, s14
	v_cmp_gt_i32_e32 vcc, s14, v6
	v_add_u32_e32 v6, -1, v4
	v_and_b32_e32 v8, 4, v17
	v_cndmask_b32_e32 v15, v10, v12, vcc
	v_min_i32_e32 v10, s15, v6
	v_cmp_gt_i32_e32 vcc, s14, v6
	v_min_i32_e32 v6, s15, v4
	v_sub_u32_e32 v2, v57, v2
	v_cndmask_b32_e32 v17, v10, v12, vcc
	v_cmp_gt_i32_e32 vcc, s14, v4
	v_lshlrev_b32_e32 v3, 1, v2
	v_lshlrev_b32_e32 v2, 3, v2
	v_cndmask_b32_e32 v20, v6, v12, vcc
	v_or_b32_e32 v6, 1, v4
	v_min_i32_e32 v10, s15, v6
	v_cmp_gt_i32_e32 vcc, s14, v6
	v_or_b32_e32 v6, 2, v4
	v_add_u32_e32 v116, v0, v11
	v_cndmask_b32_e32 v21, v10, v12, vcc
	v_min_i32_e32 v10, s15, v6
	v_cmp_gt_i32_e32 vcc, s14, v6
	v_or_b32_e32 v6, 3, v4
	v_add_u32_e32 v119, v0, v9
	v_cndmask_b32_e32 v22, v10, v12, vcc
	v_min_i32_e32 v10, s15, v6
	v_cmp_gt_i32_e32 vcc, s14, v6
	v_or_b32_e32 v6, 4, v4
	v_or_b32_e32 v0, s12, v13
	v_cndmask_b32_e32 v23, v10, v12, vcc
	v_min_i32_e32 v10, s15, v6
	v_cmp_gt_i32_e32 vcc, s14, v6
	v_or_b32_e32 v6, 5, v4
	v_and_b32_e32 v3, 62, v3
	v_cndmask_b32_e32 v24, v10, v12, vcc
	v_min_i32_e32 v10, s15, v6
	v_cmp_gt_i32_e32 vcc, s14, v6
	v_or_b32_e32 v6, 6, v4
	v_and_b32_e32 v2, 0xffffff00, v2
	v_cndmask_b32_e32 v25, v10, v12, vcc
	v_min_i32_e32 v10, s15, v6
	v_cmp_gt_i32_e32 vcc, s14, v6
	v_or_b32_e32 v6, 7, v4
	s_mul_i32 s0, s12, 0x240
	v_cndmask_b32_e32 v26, v10, v12, vcc
	v_min_i32_e32 v10, s15, v6
	v_cmp_gt_i32_e32 vcc, s14, v6
	v_or_b32_e32 v6, 8, v4
	v_lshlrev_b32_e32 v120, 3, v0
	v_cndmask_b32_e32 v27, v10, v12, vcc
	v_min_i32_e32 v10, s15, v6
	v_cmp_gt_i32_e32 vcc, s14, v6
	v_or_b32_e32 v6, 9, v4
	v_or_b32_e32 v0, s48, v13
	v_cndmask_b32_e32 v28, v10, v12, vcc
	v_min_i32_e32 v10, s15, v6
	v_cmp_gt_i32_e32 vcc, s14, v6
	v_or_b32_e32 v6, 10, v4
	v_or3_b32 v2, v2, s8, v3
	v_cndmask_b32_e32 v29, v10, v12, vcc
	v_min_i32_e32 v10, s15, v6
	v_cmp_gt_i32_e32 vcc, s14, v6
	v_or_b32_e32 v6, 11, v4
	v_lshlrev_b32_e32 v13, 3, v0
	v_cndmask_b32_e32 v30, v10, v12, vcc
	v_min_i32_e32 v10, s15, v6
	v_cmp_gt_i32_e32 vcc, s14, v6
	v_or_b32_e32 v6, 12, v4
	v_or_b32_e32 v0, s13, v53
	v_cndmask_b32_e32 v31, v10, v12, vcc
	v_min_i32_e32 v10, s15, v6
	v_cmp_gt_i32_e32 vcc, s14, v6
	v_or_b32_e32 v6, 13, v4
	v_mov_b64_e32 v[18:19], s[16:17]
	v_cndmask_b32_e32 v32, v10, v12, vcc
	v_min_i32_e32 v10, s15, v6
	v_cmp_gt_i32_e32 vcc, s14, v6
	v_or_b32_e32 v6, 14, v4
	v_ashrrev_i32_e32 v3, 31, v2
	v_cndmask_b32_e32 v33, v10, v12, vcc
	v_min_i32_e32 v10, s15, v6
	v_cmp_gt_i32_e32 vcc, s14, v6
	v_or_b32_e32 v6, 15, v4
	v_add_u32_e32 v9, 0x900, v122
	v_cndmask_b32_e32 v34, v10, v12, vcc
	v_min_i32_e32 v10, s15, v6
	v_cmp_gt_i32_e32 vcc, s14, v6
	v_add_u32_e32 v6, 16, v4
	v_add_u32_e32 v4, 17, v4
	v_cndmask_b32_e32 v35, v10, v12, vcc
	v_min_i32_e32 v10, s15, v6
	v_cmp_gt_i32_e32 vcc, s14, v6
	v_min_i32_e32 v6, s15, v4
	v_add_u32_e32 v11, 0x1200, v122
	v_cndmask_b32_e32 v36, v10, v12, vcc
	v_cmp_gt_i32_e32 vcc, s14, v4
	v_lshl_add_u64 v[2:3], v[2:3], 1, s[16:17]
	s_mov_b32 s9, 0
	v_cndmask_b32_e32 v37, v6, v12, vcc
	v_lshlrev_b32_e32 v12, 3, v53
	v_lshl_or_b32 v60, s12, 8, v12
	v_and_b32_e32 v6, 16, v7
	s_lshl_b32 s12, s49, 8
	v_or3_b32 v4, v6, s45, v109
	v_or3_b32 v6, v109, v6, s45
	s_and_b32 s12, s12, 0xc00
	v_lshl_or_b32 v4, v4, 3, v8
	v_lshl_or_b32 v62, v6, 3, v8
	v_lshl_or_b32 v6, s48, 8, v12
	v_or_b32_e32 v12, s12, v12
	v_mad_i64_i32 v[18:19], s[12:13], v0, s66, v[18:19]
	v_add_u32_e32 v0, 0x1800, v5
	v_or_b32_e32 v8, 0x100, v4
	v_or_b32_e32 v10, 0x500, v4
	v_or_b32_e32 v14, 0x900, v4
	v_or_b32_e32 v16, 0xd00, v4
	v_lshl_add_u64 v[64:65], v[18:19], 0, v[0:1]
	v_add_u32_e32 v0, 0x1810, v5
	s_mov_b64 s[46:47], -1
	v_cmp_eq_u32_e64 s[42:43], 0, v57
	s_mul_i32 s8, s50, 0x90
	v_lshl_add_u64 v[66:67], v[18:19], 0, v[0:1]
	v_mad_i64_i32 v[68:69], s[12:13], v15, s66, v[2:3]
	v_mad_i64_i32 v[70:71], s[12:13], v17, s66, v[2:3]
	v_mad_i64_i32 v[72:73], s[12:13], v20, s66, v[2:3]
	v_mad_i64_i32 v[74:75], s[12:13], v21, s66, v[2:3]
	v_mad_i64_i32 v[76:77], s[12:13], v22, s66, v[2:3]
	v_mad_i64_i32 v[78:79], s[12:13], v23, s66, v[2:3]
	v_mad_i64_i32 v[80:81], s[12:13], v24, s66, v[2:3]
	v_mad_i64_i32 v[82:83], s[12:13], v25, s66, v[2:3]
	v_mad_i64_i32 v[84:85], s[12:13], v26, s66, v[2:3]
	v_mad_i64_i32 v[86:87], s[12:13], v27, s66, v[2:3]
	v_mad_i64_i32 v[88:89], s[12:13], v28, s66, v[2:3]
	v_mad_i64_i32 v[90:91], s[12:13], v29, s66, v[2:3]
	v_mad_i64_i32 v[92:93], s[12:13], v30, s66, v[2:3]
	v_mad_i64_i32 v[94:95], s[12:13], v31, s66, v[2:3]
	v_mad_i64_i32 v[96:97], s[12:13], v32, s66, v[2:3]
	v_mad_i64_i32 v[98:99], s[12:13], v33, s66, v[2:3]
	v_mad_i64_i32 v[100:101], s[12:13], v34, s66, v[2:3]
	v_mad_i64_i32 v[102:103], s[12:13], v35, s66, v[2:3]
	v_mad_i64_i32 v[104:105], s[12:13], v36, s66, v[2:3]
	v_mad_i64_i32 v[106:107], s[12:13], v37, s66, v[2:3]
	v_add_u32_e32 v123, v121, v13
	v_lshlrev_b32_e32 v124, 1, v4
	v_lshlrev_b32_e32 v125, 1, v6
	v_lshlrev_b32_e32 v126, 1, v8
	v_lshlrev_b32_e32 v127, 1, v12
	v_lshlrev_b32_e32 v128, 1, v10
	v_lshlrev_b32_e32 v129, 1, v14
	v_lshlrev_b32_e32 v130, 1, v16
	v_add_u32_e32 v131, v9, v120
	v_add_u32_e32 v132, v11, v120
	s_waitcnt lgkmcnt(0)
	s_barrier
	s_branch .LBB0_646
